# code placement: every 32-MFMA block of the six K-loops starts 8-byte aligned (s_nop padding on the loader side, before the barrier)
# baseline (speedup 1.0000x reference)
.LBB0_306:
	ds_read_b128 v[166:169], v162
	ds_read_b128 v[170:173], v162 offset:1024
	ds_read_b128 v[174:177], v162 offset:2048
	ds_read_b128 v[180:183], v162 offset:3072
	ds_read_b128 v[184:187], v163
	ds_read_b128 v[188:191], v163 offset:1024
	ds_read_b128 v[192:195], v163 offset:2048
	ds_read_b128 v[196:199], v163 offset:3072
	s_add_u32 s30, s28, 0xfff80080
	s_addc_u32 s31, s29, -1
	s_cmp_eq_u32 s50, 28
	s_cselect_b32 s35, s3, s31
	s_cselect_b32 s34, s21, s30
	s_cselect_b32 s31, s19, s49
	s_cselect_b32 s30, s27, s48
	v_lshl_add_u64 v[160:161], s[28:29], 0, v[152:153]
	s_add_i32 m0, s33, 0xc000
	ds_read_b128 v[200:203], v164
	ds_read_b128 v[204:207], v164 offset:1024
	ds_read_b128 v[208:211], v164 offset:2048
	ds_read_b128 v[212:215], v164 offset:3072
	ds_read_b128 v[216:219], v164 offset:4096
	ds_read_b128 v[220:223], v164 offset:5120
	ds_read_b128 v[224:227], v164 offset:6144
	ds_read_b128 v[228:231], v164 offset:7168
	global_load_lds_dwordx4 v[160:161], off
	v_lshl_add_u64 v[160:161], s[28:29], 0, v[154:155]
	s_add_i32 m0, s33, 0xe000
	s_nop 0
	global_load_lds_dwordx4 v[160:161], off
	s_waitcnt vmcnt(8)
	s_waitcnt lgkmcnt(0)
	s_setprio 1
	s_barrier
	v_mfma_f32_16x16x32_bf16 v[126:129], v[166:169], v[200:203], v[126:129]
	v_mfma_f32_16x16x32_bf16 v[122:125], v[174:177], v[200:203], v[122:125]
	v_mfma_f32_16x16x32_bf16 v[110:113], v[166:169], v[208:211], v[110:113]
	v_mfma_f32_16x16x32_bf16 v[106:109], v[174:177], v[208:211], v[106:109]
	v_mfma_f32_16x16x32_bf16 v[94:97], v[166:169], v[216:219], v[94:97]
	v_mfma_f32_16x16x32_bf16 v[90:93], v[174:177], v[216:219], v[90:93]
	v_mfma_f32_16x16x32_bf16 v[78:81], v[166:169], v[224:227], v[78:81]
	v_mfma_f32_16x16x32_bf16 v[74:77], v[174:177], v[224:227], v[74:77]
	v_mfma_f32_16x16x32_bf16 v[126:129], v[170:173], v[204:207], v[126:129]
	v_mfma_f32_16x16x32_bf16 v[122:125], v[180:183], v[204:207], v[122:125]
	v_mfma_f32_16x16x32_bf16 v[110:113], v[170:173], v[212:215], v[110:113]
	v_mfma_f32_16x16x32_bf16 v[106:109], v[180:183], v[212:215], v[106:109]
	v_mfma_f32_16x16x32_bf16 v[94:97], v[170:173], v[220:223], v[94:97]
	v_mfma_f32_16x16x32_bf16 v[90:93], v[180:183], v[220:223], v[90:93]
	v_mfma_f32_16x16x32_bf16 v[78:81], v[170:173], v[228:231], v[78:81]
	v_mfma_f32_16x16x32_bf16 v[74:77], v[180:183], v[228:231], v[74:77]
	v_mfma_f32_16x16x32_bf16 v[118:121], v[184:187], v[200:203], v[118:121]
	v_mfma_f32_16x16x32_bf16 v[114:117], v[192:195], v[200:203], v[114:117]
	v_mfma_f32_16x16x32_bf16 v[102:105], v[184:187], v[208:211], v[102:105]
	v_mfma_f32_16x16x32_bf16 v[98:101], v[192:195], v[208:211], v[98:101]
	v_mfma_f32_16x16x32_bf16 v[86:89], v[184:187], v[216:219], v[86:89]
	v_mfma_f32_16x16x32_bf16 v[82:85], v[192:195], v[216:219], v[82:85]
	v_mfma_f32_16x16x32_bf16 v[70:73], v[184:187], v[224:227], v[70:73]
	v_mfma_f32_16x16x32_bf16 v[66:69], v[192:195], v[224:227], v[66:69]
	v_mfma_f32_16x16x32_bf16 v[118:121], v[188:191], v[204:207], v[118:121]
	v_mfma_f32_16x16x32_bf16 v[114:117], v[196:199], v[204:207], v[114:117]
	v_mfma_f32_16x16x32_bf16 v[102:105], v[188:191], v[212:215], v[102:105]
	v_mfma_f32_16x16x32_bf16 v[98:101], v[196:199], v[212:215], v[98:101]
	v_mfma_f32_16x16x32_bf16 v[86:89], v[188:191], v[220:223], v[86:89]
	v_mfma_f32_16x16x32_bf16 v[82:85], v[196:199], v[220:223], v[82:85]
	v_mfma_f32_16x16x32_bf16 v[70:73], v[188:191], v[228:231], v[70:73]
	v_mfma_f32_16x16x32_bf16 v[66:69], v[196:199], v[228:231], v[66:69]
	s_barrier
	s_setprio 0
	s_add_i32 s51, s45, s17
	v_lshl_add_u64 v[160:161], s[30:31], 0, v[138:139]
	s_mov_b32 m0, s51
	ds_read_b128 v[200:203], v164 offset:16384
	ds_read_b128 v[204:207], v164 offset:17408
	ds_read_b128 v[208:211], v164 offset:18432
	ds_read_b128 v[212:215], v164 offset:19456
	ds_read_b128 v[216:219], v164 offset:20480
	ds_read_b128 v[220:223], v164 offset:21504
	ds_read_b128 v[224:227], v164 offset:22528
	ds_read_b128 v[228:231], v164 offset:23552
	global_load_lds_dwordx4 v[160:161], off
	s_add_i32 m0, s51, 0x2000
	s_add_u32 s56, s30, 0x80000
	v_lshl_add_u64 v[232:233], s[30:31], 0, v[142:143]
	s_addc_u32 s57, s31, 0
	s_add_i32 s51, s47, s17
	global_load_lds_dwordx4 v[232:233], off
	v_lshl_add_u64 v[234:235], s[56:57], 0, v[138:139]
	s_mov_b32 m0, s51
	v_lshl_add_u64 v[236:237], s[34:35], 0, v[140:141]
	global_load_lds_dwordx4 v[234:235], off
	v_lshl_add_u64 v[234:235], s[56:57], 0, v[142:143]
	s_add_i32 m0, s51, 0x2000
	s_nop 0
	global_load_lds_dwordx4 v[234:235], off
	v_lshl_add_u64 v[234:235], s[34:35], 0, v[136:137]
	s_mov_b32 m0, s33
	s_nop 0
	global_load_lds_dwordx4 v[234:235], off
	s_mov_b32 m0, s36
	s_nop 0
	global_load_lds_dwordx4 v[236:237], off
	s_waitcnt vmcnt(8)
	s_waitcnt lgkmcnt(0)
	s_setprio 1
	s_barrier
	v_mfma_f32_16x16x32_bf16 v[62:65], v[166:169], v[200:203], v[62:65]
	v_mfma_f32_16x16x32_bf16 v[58:61], v[174:177], v[200:203], v[58:61]
	v_mfma_f32_16x16x32_bf16 v[46:49], v[166:169], v[208:211], v[46:49]
	v_mfma_f32_16x16x32_bf16 v[42:45], v[174:177], v[208:211], v[42:45]
	v_mfma_f32_16x16x32_bf16 v[30:33], v[166:169], v[216:219], v[30:33]
	v_mfma_f32_16x16x32_bf16 v[26:29], v[174:177], v[216:219], v[26:29]
	v_mfma_f32_16x16x32_bf16 v[14:17], v[166:169], v[224:227], v[14:17]
	v_mfma_f32_16x16x32_bf16 v[10:13], v[174:177], v[224:227], v[10:13]
	v_mfma_f32_16x16x32_bf16 v[62:65], v[170:173], v[204:207], v[62:65]
	v_mfma_f32_16x16x32_bf16 v[58:61], v[180:183], v[204:207], v[58:61]
	v_mfma_f32_16x16x32_bf16 v[46:49], v[170:173], v[212:215], v[46:49]
	v_mfma_f32_16x16x32_bf16 v[42:45], v[180:183], v[212:215], v[42:45]
	v_mfma_f32_16x16x32_bf16 v[30:33], v[170:173], v[220:223], v[30:33]
	v_mfma_f32_16x16x32_bf16 v[26:29], v[180:183], v[220:223], v[26:29]
	v_mfma_f32_16x16x32_bf16 v[14:17], v[170:173], v[228:231], v[14:17]
	v_mfma_f32_16x16x32_bf16 v[10:13], v[180:183], v[228:231], v[10:13]
	v_mfma_f32_16x16x32_bf16 v[54:57], v[184:187], v[200:203], v[54:57]
	v_mfma_f32_16x16x32_bf16 v[50:53], v[192:195], v[200:203], v[50:53]
	v_mfma_f32_16x16x32_bf16 v[38:41], v[184:187], v[208:211], v[38:41]
	v_mfma_f32_16x16x32_bf16 v[34:37], v[192:195], v[208:211], v[34:37]
	v_mfma_f32_16x16x32_bf16 v[22:25], v[184:187], v[216:219], v[22:25]
	v_mfma_f32_16x16x32_bf16 v[18:21], v[192:195], v[216:219], v[18:21]
	v_mfma_f32_16x16x32_bf16 v[6:9], v[184:187], v[224:227], v[6:9]
	v_mfma_f32_16x16x32_bf16 v[2:5], v[192:195], v[224:227], v[2:5]
	v_mfma_f32_16x16x32_bf16 v[54:57], v[188:191], v[204:207], v[54:57]
	v_mfma_f32_16x16x32_bf16 v[50:53], v[196:199], v[204:207], v[50:53]
	v_mfma_f32_16x16x32_bf16 v[38:41], v[188:191], v[212:215], v[38:41]
	v_mfma_f32_16x16x32_bf16 v[34:37], v[196:199], v[212:215], v[34:37]
	v_mfma_f32_16x16x32_bf16 v[22:25], v[188:191], v[220:223], v[22:25]
	v_mfma_f32_16x16x32_bf16 v[18:21], v[196:199], v[220:223], v[18:21]
	v_mfma_f32_16x16x32_bf16 v[6:9], v[188:191], v[228:231], v[6:9]
	v_mfma_f32_16x16x32_bf16 v[2:5], v[196:199], v[228:231], v[2:5]
	s_barrier
	s_setprio 0
	s_add_i32 s51, 0, 0x18000
	v_add_u32_e32 v144, s51, v135
	s_add_i32 s56, 0, 0x1c000
	ds_read_b128 v[166:169], v144
	ds_read_b128 v[170:173], v144 offset:1024
	ds_read_b128 v[174:177], v144 offset:2048
	ds_read_b128 v[180:183], v144 offset:3072
	v_add_u32_e32 v144, s56, v135
	ds_read_b128 v[184:187], v144
	ds_read_b128 v[188:191], v144 offset:1024
	ds_read_b128 v[192:195], v144 offset:2048
	ds_read_b128 v[196:199], v144 offset:3072
	s_add_u32 s34, s34, 0x80000
	s_addc_u32 s35, s35, 0
	s_mov_b32 m0, s37
	v_lshl_add_u64 v[238:239], s[34:35], 0, v[136:137]
	ds_read_b128 v[200:203], v164 offset:32768
	ds_read_b128 v[204:207], v164 offset:33792
	ds_read_b128 v[208:211], v164 offset:34816
	ds_read_b128 v[212:215], v164 offset:35840
	ds_read_b128 v[216:219], v164 offset:36864
	ds_read_b128 v[220:223], v164 offset:37888
	ds_read_b128 v[224:227], v164 offset:38912
	ds_read_b128 v[228:231], v164 offset:39936
	global_load_lds_dwordx4 v[238:239], off
	v_lshl_add_u64 v[238:239], s[34:35], 0, v[140:141]
	s_mov_b32 m0, s38
	s_nop 0
	global_load_lds_dwordx4 v[238:239], off
	s_waitcnt vmcnt(8)
	s_waitcnt lgkmcnt(0)
	s_setprio 1
	s_barrier
	v_mfma_f32_16x16x32_bf16 v[126:129], v[166:169], v[200:203], v[126:129]
	v_mfma_f32_16x16x32_bf16 v[122:125], v[174:177], v[200:203], v[122:125]
	v_mfma_f32_16x16x32_bf16 v[110:113], v[166:169], v[208:211], v[110:113]
	v_mfma_f32_16x16x32_bf16 v[106:109], v[174:177], v[208:211], v[106:109]
	v_mfma_f32_16x16x32_bf16 v[94:97], v[166:169], v[216:219], v[94:97]
	v_mfma_f32_16x16x32_bf16 v[90:93], v[174:177], v[216:219], v[90:93]
	v_mfma_f32_16x16x32_bf16 v[78:81], v[166:169], v[224:227], v[78:81]
	v_mfma_f32_16x16x32_bf16 v[74:77], v[174:177], v[224:227], v[74:77]
	v_mfma_f32_16x16x32_bf16 v[126:129], v[170:173], v[204:207], v[126:129]
	v_mfma_f32_16x16x32_bf16 v[122:125], v[180:183], v[204:207], v[122:125]
	v_mfma_f32_16x16x32_bf16 v[110:113], v[170:173], v[212:215], v[110:113]
	v_mfma_f32_16x16x32_bf16 v[106:109], v[180:183], v[212:215], v[106:109]
	v_mfma_f32_16x16x32_bf16 v[94:97], v[170:173], v[220:223], v[94:97]
	v_mfma_f32_16x16x32_bf16 v[90:93], v[180:183], v[220:223], v[90:93]
	v_mfma_f32_16x16x32_bf16 v[78:81], v[170:173], v[228:231], v[78:81]
	v_mfma_f32_16x16x32_bf16 v[74:77], v[180:183], v[228:231], v[74:77]
	v_mfma_f32_16x16x32_bf16 v[118:121], v[184:187], v[200:203], v[118:121]
	v_mfma_f32_16x16x32_bf16 v[114:117], v[192:195], v[200:203], v[114:117]
	v_mfma_f32_16x16x32_bf16 v[102:105], v[184:187], v[208:211], v[102:105]
	v_mfma_f32_16x16x32_bf16 v[98:101], v[192:195], v[208:211], v[98:101]
	v_mfma_f32_16x16x32_bf16 v[86:89], v[184:187], v[216:219], v[86:89]
	v_mfma_f32_16x16x32_bf16 v[82:85], v[192:195], v[216:219], v[82:85]
	v_mfma_f32_16x16x32_bf16 v[70:73], v[184:187], v[224:227], v[70:73]
	v_mfma_f32_16x16x32_bf16 v[66:69], v[192:195], v[224:227], v[66:69]
	v_mfma_f32_16x16x32_bf16 v[118:121], v[188:191], v[204:207], v[118:121]
	v_mfma_f32_16x16x32_bf16 v[114:117], v[196:199], v[204:207], v[114:117]
	v_mfma_f32_16x16x32_bf16 v[102:105], v[188:191], v[212:215], v[102:105]
	v_mfma_f32_16x16x32_bf16 v[98:101], v[196:199], v[212:215], v[98:101]
	v_mfma_f32_16x16x32_bf16 v[86:89], v[188:191], v[220:223], v[86:89]
	v_mfma_f32_16x16x32_bf16 v[82:85], v[196:199], v[220:223], v[82:85]
	v_mfma_f32_16x16x32_bf16 v[70:73], v[188:191], v[228:231], v[70:73]
	v_mfma_f32_16x16x32_bf16 v[66:69], v[196:199], v[228:231], v[66:69]
	s_barrier
	s_setprio 0
	s_add_i32 s34, s51, s17
	v_lshl_add_u64 v[160:161], v[160:161], 0, s[6:7]
	s_mov_b32 m0, s34
	ds_read_b128 v[200:203], v164 offset:49152
	ds_read_b128 v[204:207], v164 offset:50176
	ds_read_b128 v[208:211], v164 offset:51200
	ds_read_b128 v[212:215], v164 offset:52224
	ds_read_b128 v[216:219], v164 offset:53248
	ds_read_b128 v[220:223], v164 offset:54272
	ds_read_b128 v[224:227], v164 offset:55296
	ds_read_b128 v[228:231], v164 offset:56320
	global_load_lds_dwordx4 v[160:161], off
	s_add_i32 m0, s34, 0x2000
	s_add_u32 s30, s30, 0x80080
	v_lshl_add_u64 v[160:161], v[232:233], 0, s[6:7]
	s_addc_u32 s31, s31, 0
	s_add_i32 s34, s56, s17
	global_load_lds_dwordx4 v[160:161], off
	v_lshl_add_u64 v[160:161], s[30:31], 0, v[138:139]
	s_mov_b32 m0, s34
	s_nop 0
	global_load_lds_dwordx4 v[160:161], off
	v_lshl_add_u64 v[160:161], s[30:31], 0, v[142:143]
	s_add_i32 m0, s34, 0x2000
	s_nop 0
	global_load_lds_dwordx4 v[160:161], off
	v_lshl_add_u64 v[160:161], v[234:235], 0, s[6:7]
	s_mov_b32 m0, s40
	s_nop 0
	global_load_lds_dwordx4 v[160:161], off
	v_lshl_add_u64 v[160:161], v[236:237], 0, s[6:7]
	s_mov_b32 m0, s41
	s_nop 0
	global_load_lds_dwordx4 v[160:161], off
	s_waitcnt vmcnt(8)
	s_waitcnt lgkmcnt(0)
	s_nop 0
	s_setprio 1
	s_barrier
	v_mfma_f32_16x16x32_bf16 v[62:65], v[166:169], v[200:203], v[62:65]
	v_mfma_f32_16x16x32_bf16 v[58:61], v[174:177], v[200:203], v[58:61]
	v_mfma_f32_16x16x32_bf16 v[46:49], v[166:169], v[208:211], v[46:49]
	v_mfma_f32_16x16x32_bf16 v[42:45], v[174:177], v[208:211], v[42:45]
	v_mfma_f32_16x16x32_bf16 v[30:33], v[166:169], v[216:219], v[30:33]
	v_mfma_f32_16x16x32_bf16 v[26:29], v[174:177], v[216:219], v[26:29]
	v_mfma_f32_16x16x32_bf16 v[14:17], v[166:169], v[224:227], v[14:17]
	v_mfma_f32_16x16x32_bf16 v[10:13], v[174:177], v[224:227], v[10:13]
	v_mfma_f32_16x16x32_bf16 v[62:65], v[170:173], v[204:207], v[62:65]
	v_mfma_f32_16x16x32_bf16 v[58:61], v[180:183], v[204:207], v[58:61]
	v_mfma_f32_16x16x32_bf16 v[46:49], v[170:173], v[212:215], v[46:49]
	v_mfma_f32_16x16x32_bf16 v[42:45], v[180:183], v[212:215], v[42:45]
	v_mfma_f32_16x16x32_bf16 v[30:33], v[170:173], v[220:223], v[30:33]
	v_mfma_f32_16x16x32_bf16 v[26:29], v[180:183], v[220:223], v[26:29]
	v_mfma_f32_16x16x32_bf16 v[14:17], v[170:173], v[228:231], v[14:17]
	v_mfma_f32_16x16x32_bf16 v[10:13], v[180:183], v[228:231], v[10:13]
	v_mfma_f32_16x16x32_bf16 v[54:57], v[184:187], v[200:203], v[54:57]
	v_mfma_f32_16x16x32_bf16 v[50:53], v[192:195], v[200:203], v[50:53]
	v_mfma_f32_16x16x32_bf16 v[38:41], v[184:187], v[208:211], v[38:41]
	v_mfma_f32_16x16x32_bf16 v[34:37], v[192:195], v[208:211], v[34:37]
	v_mfma_f32_16x16x32_bf16 v[22:25], v[184:187], v[216:219], v[22:25]
	v_mfma_f32_16x16x32_bf16 v[18:21], v[192:195], v[216:219], v[18:21]
	v_mfma_f32_16x16x32_bf16 v[6:9], v[184:187], v[224:227], v[6:9]
	v_mfma_f32_16x16x32_bf16 v[2:5], v[192:195], v[224:227], v[2:5]
	v_mfma_f32_16x16x32_bf16 v[54:57], v[188:191], v[204:207], v[54:57]
	v_mfma_f32_16x16x32_bf16 v[50:53], v[196:199], v[204:207], v[50:53]
	v_mfma_f32_16x16x32_bf16 v[38:41], v[188:191], v[212:215], v[38:41]
	v_mfma_f32_16x16x32_bf16 v[34:37], v[196:199], v[212:215], v[34:37]
	v_mfma_f32_16x16x32_bf16 v[22:25], v[188:191], v[220:223], v[22:25]
	v_mfma_f32_16x16x32_bf16 v[18:21], v[196:199], v[220:223], v[18:21]
	v_mfma_f32_16x16x32_bf16 v[6:9], v[188:191], v[228:231], v[6:9]
	v_mfma_f32_16x16x32_bf16 v[2:5], v[196:199], v[228:231], v[2:5]
	s_barrier
	s_setprio 0
	s_add_i32 s50, s50, 2
	s_add_u32 s28, s28, 0x100
	s_addc_u32 s29, s29, 0
	s_add_u32 s48, s48, 0x100
	s_addc_u32 s49, s49, 0
	s_cmp_gt_u32 s50, 29
	s_cbranch_scc0 .LBB0_306
	s_and_b64 vcc, exec, s[8:9]
	s_cbranch_vccz .LBB0_314
	s_barrier
	v_lshl_add_u32 v160, s26, 8, v133
	s_cmp_gt_i32 s2, 35
	s_mov_b64 s[26:27], -1
	s_cbranch_scc1 .LBB0_315

.LBB0_986:
	ds_read_b128 v[148:151], v155
	ds_read_b128 v[158:161], v155 offset:1024
	ds_read_b128 v[162:165], v155 offset:2048
	ds_read_b128 v[166:169], v155 offset:3072
	ds_read_b128 v[170:173], v156
	ds_read_b128 v[174:177], v156 offset:1024
	ds_read_b128 v[180:183], v156 offset:2048
	ds_read_b128 v[184:187], v156 offset:3072
	s_add_u32 s26, s24, 0xfffc0080
	s_addc_u32 s27, s25, -1
	s_cmp_eq_u32 s49, 12
	s_cselect_b32 s29, s17, s27
	s_cselect_b32 s28, s45, s26
	s_cselect_b32 s27, s15, s48
	s_cselect_b32 s26, s46, s47
	v_lshl_add_u64 v[220:221], s[24:25], 0, v[138:139]
	s_add_i32 m0, s23, 0xc000
	ds_read_b128 v[188:191], v157
	ds_read_b128 v[192:195], v157 offset:1024
	ds_read_b128 v[196:199], v157 offset:2048
	ds_read_b128 v[200:203], v157 offset:3072
	ds_read_b128 v[204:207], v157 offset:4096
	ds_read_b128 v[208:211], v157 offset:5120
	ds_read_b128 v[212:215], v157 offset:6144
	ds_read_b128 v[216:219], v157 offset:7168
	global_load_lds_dwordx4 v[220:221], off
	v_lshl_add_u64 v[220:221], s[24:25], 0, v[140:141]
	s_add_i32 m0, s23, 0xe000
	s_nop 0
	global_load_lds_dwordx4 v[220:221], off
	s_waitcnt vmcnt(8)
	s_waitcnt lgkmcnt(0)
	s_nop 0
	s_setprio 1
	s_barrier
	v_mfma_f32_16x16x32_bf16 v[126:129], v[148:151], v[188:191], v[126:129]
	v_mfma_f32_16x16x32_bf16 v[122:125], v[162:165], v[188:191], v[122:125]
	v_mfma_f32_16x16x32_bf16 v[110:113], v[148:151], v[196:199], v[110:113]
	v_mfma_f32_16x16x32_bf16 v[106:109], v[162:165], v[196:199], v[106:109]
	v_mfma_f32_16x16x32_bf16 v[94:97], v[148:151], v[204:207], v[94:97]
	v_mfma_f32_16x16x32_bf16 v[90:93], v[162:165], v[204:207], v[90:93]
	v_mfma_f32_16x16x32_bf16 v[78:81], v[148:151], v[212:215], v[78:81]
	v_mfma_f32_16x16x32_bf16 v[74:77], v[162:165], v[212:215], v[74:77]
	v_mfma_f32_16x16x32_bf16 v[126:129], v[158:161], v[192:195], v[126:129]
	v_mfma_f32_16x16x32_bf16 v[122:125], v[166:169], v[192:195], v[122:125]
	v_mfma_f32_16x16x32_bf16 v[110:113], v[158:161], v[200:203], v[110:113]
	v_mfma_f32_16x16x32_bf16 v[106:109], v[166:169], v[200:203], v[106:109]
	v_mfma_f32_16x16x32_bf16 v[94:97], v[158:161], v[208:211], v[94:97]
	v_mfma_f32_16x16x32_bf16 v[90:93], v[166:169], v[208:211], v[90:93]
	v_mfma_f32_16x16x32_bf16 v[78:81], v[158:161], v[216:219], v[78:81]
	v_mfma_f32_16x16x32_bf16 v[74:77], v[166:169], v[216:219], v[74:77]
	v_mfma_f32_16x16x32_bf16 v[118:121], v[170:173], v[188:191], v[118:121]
	v_mfma_f32_16x16x32_bf16 v[114:117], v[180:183], v[188:191], v[114:117]
	v_mfma_f32_16x16x32_bf16 v[102:105], v[170:173], v[196:199], v[102:105]
	v_mfma_f32_16x16x32_bf16 v[98:101], v[180:183], v[196:199], v[98:101]
	v_mfma_f32_16x16x32_bf16 v[86:89], v[170:173], v[204:207], v[86:89]
	v_mfma_f32_16x16x32_bf16 v[82:85], v[180:183], v[204:207], v[82:85]
	v_mfma_f32_16x16x32_bf16 v[70:73], v[170:173], v[212:215], v[70:73]
	v_mfma_f32_16x16x32_bf16 v[66:69], v[180:183], v[212:215], v[66:69]
	v_mfma_f32_16x16x32_bf16 v[118:121], v[174:177], v[192:195], v[118:121]
	v_mfma_f32_16x16x32_bf16 v[114:117], v[184:187], v[192:195], v[114:117]
	v_mfma_f32_16x16x32_bf16 v[102:105], v[174:177], v[200:203], v[102:105]
	v_mfma_f32_16x16x32_bf16 v[98:101], v[184:187], v[200:203], v[98:101]
	v_mfma_f32_16x16x32_bf16 v[86:89], v[174:177], v[208:211], v[86:89]
	v_mfma_f32_16x16x32_bf16 v[82:85], v[184:187], v[208:211], v[82:85]
	v_mfma_f32_16x16x32_bf16 v[70:73], v[174:177], v[216:219], v[70:73]
	v_mfma_f32_16x16x32_bf16 v[66:69], v[184:187], v[216:219], v[66:69]
	s_barrier
	s_setprio 0
	s_add_i32 s50, s42, s30
	v_lshl_add_u64 v[220:221], s[26:27], 0, v[134:135]
	s_mov_b32 m0, s50
	ds_read_b128 v[188:191], v157 offset:16384
	ds_read_b128 v[192:195], v157 offset:17408
	ds_read_b128 v[196:199], v157 offset:18432
	ds_read_b128 v[200:203], v157 offset:19456
	ds_read_b128 v[204:207], v157 offset:20480
	ds_read_b128 v[208:211], v157 offset:21504
	ds_read_b128 v[212:215], v157 offset:22528
	ds_read_b128 v[216:219], v157 offset:23552
	global_load_lds_dwordx4 v[220:221], off
	s_add_i32 m0, s50, 0x2000
	s_add_u32 s50, s26, 0x40000
	v_lshl_add_u64 v[222:223], s[26:27], 0, v[130:131]
	s_addc_u32 s51, s27, 0
	s_add_i32 s56, s43, s30
	global_load_lds_dwordx4 v[222:223], off
	v_lshl_add_u64 v[224:225], s[50:51], 0, v[134:135]
	s_mov_b32 m0, s56
	v_lshl_add_u64 v[226:227], s[28:29], 0, v[132:133]
	global_load_lds_dwordx4 v[224:225], off
	v_lshl_add_u64 v[224:225], s[50:51], 0, v[130:131]
	s_add_i32 m0, s56, 0x2000
	s_nop 0
	global_load_lds_dwordx4 v[224:225], off
	v_lshl_add_u64 v[224:225], s[28:29], 0, v[136:137]
	s_mov_b32 m0, s23
	s_nop 0
	global_load_lds_dwordx4 v[224:225], off
	s_mov_b32 m0, s34
	s_nop 0
	global_load_lds_dwordx4 v[226:227], off
	s_waitcnt vmcnt(8)
	s_waitcnt lgkmcnt(0)
	s_setprio 1
	s_barrier
	v_mfma_f32_16x16x32_bf16 v[62:65], v[148:151], v[188:191], v[62:65]
	v_mfma_f32_16x16x32_bf16 v[58:61], v[162:165], v[188:191], v[58:61]
	v_mfma_f32_16x16x32_bf16 v[46:49], v[148:151], v[196:199], v[46:49]
	v_mfma_f32_16x16x32_bf16 v[42:45], v[162:165], v[196:199], v[42:45]
	v_mfma_f32_16x16x32_bf16 v[30:33], v[148:151], v[204:207], v[30:33]
	v_mfma_f32_16x16x32_bf16 v[26:29], v[162:165], v[204:207], v[26:29]
	v_mfma_f32_16x16x32_bf16 v[14:17], v[148:151], v[212:215], v[14:17]
	v_mfma_f32_16x16x32_bf16 v[10:13], v[162:165], v[212:215], v[10:13]
	v_mfma_f32_16x16x32_bf16 v[62:65], v[158:161], v[192:195], v[62:65]
	v_mfma_f32_16x16x32_bf16 v[58:61], v[166:169], v[192:195], v[58:61]
	v_mfma_f32_16x16x32_bf16 v[46:49], v[158:161], v[200:203], v[46:49]
	v_mfma_f32_16x16x32_bf16 v[42:45], v[166:169], v[200:203], v[42:45]
	v_mfma_f32_16x16x32_bf16 v[30:33], v[158:161], v[208:211], v[30:33]
	v_mfma_f32_16x16x32_bf16 v[26:29], v[166:169], v[208:211], v[26:29]
	v_mfma_f32_16x16x32_bf16 v[14:17], v[158:161], v[216:219], v[14:17]
	v_mfma_f32_16x16x32_bf16 v[10:13], v[166:169], v[216:219], v[10:13]
	v_mfma_f32_16x16x32_bf16 v[54:57], v[170:173], v[188:191], v[54:57]
	v_mfma_f32_16x16x32_bf16 v[50:53], v[180:183], v[188:191], v[50:53]
	v_mfma_f32_16x16x32_bf16 v[38:41], v[170:173], v[196:199], v[38:41]
	v_mfma_f32_16x16x32_bf16 v[34:37], v[180:183], v[196:199], v[34:37]
	v_mfma_f32_16x16x32_bf16 v[22:25], v[170:173], v[204:207], v[22:25]
	v_mfma_f32_16x16x32_bf16 v[18:21], v[180:183], v[204:207], v[18:21]
	v_mfma_f32_16x16x32_bf16 v[6:9], v[170:173], v[212:215], v[6:9]
	v_mfma_f32_16x16x32_bf16 v[2:5], v[180:183], v[212:215], v[2:5]
	v_mfma_f32_16x16x32_bf16 v[54:57], v[174:177], v[192:195], v[54:57]
	v_mfma_f32_16x16x32_bf16 v[50:53], v[184:187], v[192:195], v[50:53]
	v_mfma_f32_16x16x32_bf16 v[38:41], v[174:177], v[200:203], v[38:41]
	v_mfma_f32_16x16x32_bf16 v[34:37], v[184:187], v[200:203], v[34:37]
	v_mfma_f32_16x16x32_bf16 v[22:25], v[174:177], v[208:211], v[22:25]
	v_mfma_f32_16x16x32_bf16 v[18:21], v[184:187], v[208:211], v[18:21]
	v_mfma_f32_16x16x32_bf16 v[6:9], v[174:177], v[216:219], v[6:9]
	v_mfma_f32_16x16x32_bf16 v[2:5], v[184:187], v[216:219], v[2:5]
	s_barrier
	s_setprio 0
	s_add_i32 s50, 0, 0x18000
	s_add_i32 s51, 0, 0x1c000
	v_add_u32_e32 v166, s50, v153
	v_add_u32_e32 v179, s51, v153
	ds_read_b128 v[148:151], v166
	ds_read_b128 v[158:161], v166 offset:1024
	ds_read_b128 v[162:165], v166 offset:2048
	ds_read_b128 v[166:169], v166 offset:3072
	ds_read_b128 v[170:173], v179
	ds_read_b128 v[174:177], v179 offset:1024
	ds_read_b128 v[180:183], v179 offset:2048
	ds_read_b128 v[184:187], v179 offset:3072
	s_add_u32 s28, s28, 0x40000
	s_addc_u32 s29, s29, 0
	s_mov_b32 m0, s35
	v_lshl_add_u64 v[228:229], s[28:29], 0, v[136:137]
	ds_read_b128 v[188:191], v157 offset:32768
	ds_read_b128 v[192:195], v157 offset:33792
	ds_read_b128 v[196:199], v157 offset:34816
	ds_read_b128 v[200:203], v157 offset:35840
	ds_read_b128 v[204:207], v157 offset:36864
	ds_read_b128 v[208:211], v157 offset:37888
	ds_read_b128 v[212:215], v157 offset:38912
	ds_read_b128 v[216:219], v157 offset:39936
	global_load_lds_dwordx4 v[228:229], off
	v_lshl_add_u64 v[228:229], s[28:29], 0, v[132:133]
	s_mov_b32 m0, s36
	s_nop 0
	global_load_lds_dwordx4 v[228:229], off
	s_waitcnt vmcnt(8)
	s_waitcnt lgkmcnt(0)
	s_setprio 1
	s_barrier
	v_mfma_f32_16x16x32_bf16 v[126:129], v[148:151], v[188:191], v[126:129]
	v_mfma_f32_16x16x32_bf16 v[122:125], v[162:165], v[188:191], v[122:125]
	v_mfma_f32_16x16x32_bf16 v[110:113], v[148:151], v[196:199], v[110:113]
	v_mfma_f32_16x16x32_bf16 v[106:109], v[162:165], v[196:199], v[106:109]
	v_mfma_f32_16x16x32_bf16 v[94:97], v[148:151], v[204:207], v[94:97]
	v_mfma_f32_16x16x32_bf16 v[90:93], v[162:165], v[204:207], v[90:93]
	v_mfma_f32_16x16x32_bf16 v[78:81], v[148:151], v[212:215], v[78:81]
	v_mfma_f32_16x16x32_bf16 v[74:77], v[162:165], v[212:215], v[74:77]
	v_mfma_f32_16x16x32_bf16 v[126:129], v[158:161], v[192:195], v[126:129]
	v_mfma_f32_16x16x32_bf16 v[122:125], v[166:169], v[192:195], v[122:125]
	v_mfma_f32_16x16x32_bf16 v[110:113], v[158:161], v[200:203], v[110:113]
	v_mfma_f32_16x16x32_bf16 v[106:109], v[166:169], v[200:203], v[106:109]
	v_mfma_f32_16x16x32_bf16 v[94:97], v[158:161], v[208:211], v[94:97]
	v_mfma_f32_16x16x32_bf16 v[90:93], v[166:169], v[208:211], v[90:93]
	v_mfma_f32_16x16x32_bf16 v[78:81], v[158:161], v[216:219], v[78:81]
	v_mfma_f32_16x16x32_bf16 v[74:77], v[166:169], v[216:219], v[74:77]
	v_mfma_f32_16x16x32_bf16 v[118:121], v[170:173], v[188:191], v[118:121]
	v_mfma_f32_16x16x32_bf16 v[114:117], v[180:183], v[188:191], v[114:117]
	v_mfma_f32_16x16x32_bf16 v[102:105], v[170:173], v[196:199], v[102:105]
	v_mfma_f32_16x16x32_bf16 v[98:101], v[180:183], v[196:199], v[98:101]
	v_mfma_f32_16x16x32_bf16 v[86:89], v[170:173], v[204:207], v[86:89]
	v_mfma_f32_16x16x32_bf16 v[82:85], v[180:183], v[204:207], v[82:85]
	v_mfma_f32_16x16x32_bf16 v[70:73], v[170:173], v[212:215], v[70:73]
	v_mfma_f32_16x16x32_bf16 v[66:69], v[180:183], v[212:215], v[66:69]
	v_mfma_f32_16x16x32_bf16 v[118:121], v[174:177], v[192:195], v[118:121]
	v_mfma_f32_16x16x32_bf16 v[114:117], v[184:187], v[192:195], v[114:117]
	v_mfma_f32_16x16x32_bf16 v[102:105], v[174:177], v[200:203], v[102:105]
	v_mfma_f32_16x16x32_bf16 v[98:101], v[184:187], v[200:203], v[98:101]
	v_mfma_f32_16x16x32_bf16 v[86:89], v[174:177], v[208:211], v[86:89]
	v_mfma_f32_16x16x32_bf16 v[82:85], v[184:187], v[208:211], v[82:85]
	v_mfma_f32_16x16x32_bf16 v[70:73], v[174:177], v[216:219], v[70:73]
	v_mfma_f32_16x16x32_bf16 v[66:69], v[184:187], v[216:219], v[66:69]
	s_barrier
	s_setprio 0
	s_add_i32 s28, s50, s30
	v_lshl_add_u64 v[220:221], v[220:221], 0, s[4:5]
	s_mov_b32 m0, s28
	ds_read_b128 v[188:191], v157 offset:49152
	ds_read_b128 v[192:195], v157 offset:50176
	ds_read_b128 v[196:199], v157 offset:51200
	ds_read_b128 v[200:203], v157 offset:52224
	ds_read_b128 v[204:207], v157 offset:53248
	ds_read_b128 v[208:211], v157 offset:54272
	ds_read_b128 v[212:215], v157 offset:55296
	ds_read_b128 v[216:219], v157 offset:56320
	global_load_lds_dwordx4 v[220:221], off
	s_add_i32 m0, s28, 0x2000
	s_add_u32 s26, s26, 0x40080
	v_lshl_add_u64 v[220:221], v[222:223], 0, s[4:5]
	s_addc_u32 s27, s27, 0
	s_add_i32 s28, s51, s30
	global_load_lds_dwordx4 v[220:221], off
	v_lshl_add_u64 v[220:221], s[26:27], 0, v[134:135]
	s_mov_b32 m0, s28
	s_nop 0
	global_load_lds_dwordx4 v[220:221], off
	v_lshl_add_u64 v[220:221], s[26:27], 0, v[130:131]
	s_add_i32 m0, s28, 0x2000
	s_nop 0
	global_load_lds_dwordx4 v[220:221], off
	v_lshl_add_u64 v[220:221], v[224:225], 0, s[4:5]
	s_mov_b32 m0, s38
	s_nop 0
	global_load_lds_dwordx4 v[220:221], off
	v_lshl_add_u64 v[220:221], v[226:227], 0, s[4:5]
	s_mov_b32 m0, s39
	s_nop 0
	global_load_lds_dwordx4 v[220:221], off
	s_waitcnt vmcnt(8)
	s_waitcnt lgkmcnt(0)
	s_nop 0
	s_setprio 1
	s_barrier
	v_mfma_f32_16x16x32_bf16 v[62:65], v[148:151], v[188:191], v[62:65]
	v_mfma_f32_16x16x32_bf16 v[58:61], v[162:165], v[188:191], v[58:61]
	v_mfma_f32_16x16x32_bf16 v[46:49], v[148:151], v[196:199], v[46:49]
	v_mfma_f32_16x16x32_bf16 v[42:45], v[162:165], v[196:199], v[42:45]
	v_mfma_f32_16x16x32_bf16 v[30:33], v[148:151], v[204:207], v[30:33]
	v_mfma_f32_16x16x32_bf16 v[26:29], v[162:165], v[204:207], v[26:29]
	v_mfma_f32_16x16x32_bf16 v[14:17], v[148:151], v[212:215], v[14:17]
	v_mfma_f32_16x16x32_bf16 v[10:13], v[162:165], v[212:215], v[10:13]
	v_mfma_f32_16x16x32_bf16 v[62:65], v[158:161], v[192:195], v[62:65]
	v_mfma_f32_16x16x32_bf16 v[58:61], v[166:169], v[192:195], v[58:61]
	v_mfma_f32_16x16x32_bf16 v[46:49], v[158:161], v[200:203], v[46:49]
	v_mfma_f32_16x16x32_bf16 v[42:45], v[166:169], v[200:203], v[42:45]
	v_mfma_f32_16x16x32_bf16 v[30:33], v[158:161], v[208:211], v[30:33]
	v_mfma_f32_16x16x32_bf16 v[26:29], v[166:169], v[208:211], v[26:29]
	v_mfma_f32_16x16x32_bf16 v[14:17], v[158:161], v[216:219], v[14:17]
	v_mfma_f32_16x16x32_bf16 v[10:13], v[166:169], v[216:219], v[10:13]
	v_mfma_f32_16x16x32_bf16 v[54:57], v[170:173], v[188:191], v[54:57]
	v_mfma_f32_16x16x32_bf16 v[50:53], v[180:183], v[188:191], v[50:53]
	v_mfma_f32_16x16x32_bf16 v[38:41], v[170:173], v[196:199], v[38:41]
	v_mfma_f32_16x16x32_bf16 v[34:37], v[180:183], v[196:199], v[34:37]
	v_mfma_f32_16x16x32_bf16 v[22:25], v[170:173], v[204:207], v[22:25]
	v_mfma_f32_16x16x32_bf16 v[18:21], v[180:183], v[204:207], v[18:21]
	v_mfma_f32_16x16x32_bf16 v[6:9], v[170:173], v[212:215], v[6:9]
	v_mfma_f32_16x16x32_bf16 v[2:5], v[180:183], v[212:215], v[2:5]
	v_mfma_f32_16x16x32_bf16 v[54:57], v[174:177], v[192:195], v[54:57]
	v_mfma_f32_16x16x32_bf16 v[50:53], v[184:187], v[192:195], v[50:53]
	v_mfma_f32_16x16x32_bf16 v[38:41], v[174:177], v[200:203], v[38:41]
	v_mfma_f32_16x16x32_bf16 v[34:37], v[184:187], v[200:203], v[34:37]
	v_mfma_f32_16x16x32_bf16 v[22:25], v[174:177], v[208:211], v[22:25]
	v_mfma_f32_16x16x32_bf16 v[18:21], v[184:187], v[208:211], v[18:21]
	v_mfma_f32_16x16x32_bf16 v[6:9], v[174:177], v[216:219], v[6:9]
	v_mfma_f32_16x16x32_bf16 v[2:5], v[184:187], v[216:219], v[2:5]
	s_barrier
	s_setprio 0
	s_add_i32 s49, s49, 2
	s_add_u32 s24, s24, 0x100
	s_addc_u32 s25, s25, 0
	s_add_u32 s47, s47, 0x100
	s_addc_u32 s48, s48, 0
	s_cmp_gt_u32 s49, 13
	s_cbranch_scc0 .LBB0_986
	s_and_b64 vcc, exec, s[8:9]
	s_cbranch_vccz .LBB0_989
	s_barrier

.LBB0_1054:
	ds_read_b128 v[148:151], v155
	ds_read_b128 v[158:161], v155 offset:1024
	ds_read_b128 v[162:165], v155 offset:2048
	ds_read_b128 v[166:169], v155 offset:3072
	ds_read_b128 v[170:173], v156
	ds_read_b128 v[174:177], v156 offset:1024
	ds_read_b128 v[180:183], v156 offset:2048
	ds_read_b128 v[184:187], v156 offset:3072
	s_add_u32 s26, s24, 0xfffc0080
	s_addc_u32 s27, s25, -1
	s_cmp_eq_u32 s50, 12
	s_cselect_b32 s29, s17, s27
	s_cselect_b32 s28, s46, s26
	s_cselect_b32 s27, s15, s49
	s_cselect_b32 s26, s47, s48
	v_lshl_add_u64 v[220:221], s[24:25], 0, v[138:139]
	s_add_i32 m0, s23, 0xc000
	ds_read_b128 v[188:191], v157
	ds_read_b128 v[192:195], v157 offset:1024
	ds_read_b128 v[196:199], v157 offset:2048
	ds_read_b128 v[200:203], v157 offset:3072
	ds_read_b128 v[204:207], v157 offset:4096
	ds_read_b128 v[208:211], v157 offset:5120
	ds_read_b128 v[212:215], v157 offset:6144
	ds_read_b128 v[216:219], v157 offset:7168
	global_load_lds_dwordx4 v[220:221], off
	v_lshl_add_u64 v[220:221], s[24:25], 0, v[140:141]
	s_add_i32 m0, s23, 0xe000
	s_nop 0
	global_load_lds_dwordx4 v[220:221], off
	s_waitcnt vmcnt(8)
	s_waitcnt lgkmcnt(0)
	s_setprio 1
	s_barrier
	v_mfma_f32_16x16x32_bf16 v[118:121], v[148:151], v[188:191], v[118:121]
	v_mfma_f32_16x16x32_bf16 v[114:117], v[162:165], v[188:191], v[114:117]
	v_mfma_f32_16x16x32_bf16 v[102:105], v[148:151], v[196:199], v[102:105]
	v_mfma_f32_16x16x32_bf16 v[98:101], v[162:165], v[196:199], v[98:101]
	v_mfma_f32_16x16x32_bf16 v[86:89], v[148:151], v[204:207], v[86:89]
	v_mfma_f32_16x16x32_bf16 v[82:85], v[162:165], v[204:207], v[82:85]
	v_mfma_f32_16x16x32_bf16 v[70:73], v[148:151], v[212:215], v[70:73]
	v_mfma_f32_16x16x32_bf16 v[66:69], v[162:165], v[212:215], v[66:69]
	v_mfma_f32_16x16x32_bf16 v[118:121], v[158:161], v[192:195], v[118:121]
	v_mfma_f32_16x16x32_bf16 v[114:117], v[166:169], v[192:195], v[114:117]
	v_mfma_f32_16x16x32_bf16 v[102:105], v[158:161], v[200:203], v[102:105]
	v_mfma_f32_16x16x32_bf16 v[98:101], v[166:169], v[200:203], v[98:101]
	v_mfma_f32_16x16x32_bf16 v[86:89], v[158:161], v[208:211], v[86:89]
	v_mfma_f32_16x16x32_bf16 v[82:85], v[166:169], v[208:211], v[82:85]
	v_mfma_f32_16x16x32_bf16 v[70:73], v[158:161], v[216:219], v[70:73]
	v_mfma_f32_16x16x32_bf16 v[66:69], v[166:169], v[216:219], v[66:69]
	v_mfma_f32_16x16x32_bf16 v[126:129], v[170:173], v[188:191], v[126:129]
	v_mfma_f32_16x16x32_bf16 v[122:125], v[180:183], v[188:191], v[122:125]
	v_mfma_f32_16x16x32_bf16 v[110:113], v[170:173], v[196:199], v[110:113]
	v_mfma_f32_16x16x32_bf16 v[106:109], v[180:183], v[196:199], v[106:109]
	v_mfma_f32_16x16x32_bf16 v[94:97], v[170:173], v[204:207], v[94:97]
	v_mfma_f32_16x16x32_bf16 v[90:93], v[180:183], v[204:207], v[90:93]
	v_mfma_f32_16x16x32_bf16 v[78:81], v[170:173], v[212:215], v[78:81]
	v_mfma_f32_16x16x32_bf16 v[74:77], v[180:183], v[212:215], v[74:77]
	v_mfma_f32_16x16x32_bf16 v[126:129], v[174:177], v[192:195], v[126:129]
	v_mfma_f32_16x16x32_bf16 v[122:125], v[184:187], v[192:195], v[122:125]
	v_mfma_f32_16x16x32_bf16 v[110:113], v[174:177], v[200:203], v[110:113]
	v_mfma_f32_16x16x32_bf16 v[106:109], v[184:187], v[200:203], v[106:109]
	v_mfma_f32_16x16x32_bf16 v[94:97], v[174:177], v[208:211], v[94:97]
	v_mfma_f32_16x16x32_bf16 v[90:93], v[184:187], v[208:211], v[90:93]
	v_mfma_f32_16x16x32_bf16 v[78:81], v[174:177], v[216:219], v[78:81]
	v_mfma_f32_16x16x32_bf16 v[74:77], v[184:187], v[216:219], v[74:77]
	s_barrier
	s_setprio 0
	s_add_i32 s51, s42, s30
	v_lshl_add_u64 v[220:221], s[26:27], 0, v[134:135]
	s_mov_b32 m0, s51
	ds_read_b128 v[188:191], v157 offset:16384
	ds_read_b128 v[192:195], v157 offset:17408
	ds_read_b128 v[196:199], v157 offset:18432
	ds_read_b128 v[200:203], v157 offset:19456
	ds_read_b128 v[204:207], v157 offset:20480
	ds_read_b128 v[208:211], v157 offset:21504
	ds_read_b128 v[212:215], v157 offset:22528
	ds_read_b128 v[216:219], v157 offset:23552
	global_load_lds_dwordx4 v[220:221], off
	s_add_i32 m0, s51, 0x2000
	s_add_u32 s56, s26, 0x40000
	v_lshl_add_u64 v[222:223], s[26:27], 0, v[130:131]
	s_addc_u32 s57, s27, 0
	s_add_i32 s51, s43, s30
	global_load_lds_dwordx4 v[222:223], off
	v_lshl_add_u64 v[224:225], s[56:57], 0, v[134:135]
	s_mov_b32 m0, s51
	v_lshl_add_u64 v[226:227], s[28:29], 0, v[132:133]
	global_load_lds_dwordx4 v[224:225], off
	v_lshl_add_u64 v[224:225], s[56:57], 0, v[130:131]
	s_add_i32 m0, s51, 0x2000
	s_nop 0
	global_load_lds_dwordx4 v[224:225], off
	v_lshl_add_u64 v[224:225], s[28:29], 0, v[136:137]
	s_mov_b32 m0, s23
	s_nop 0
	global_load_lds_dwordx4 v[224:225], off
	s_mov_b32 m0, s34
	s_nop 0
	global_load_lds_dwordx4 v[226:227], off
	s_waitcnt vmcnt(8)
	s_waitcnt lgkmcnt(0)
	s_setprio 1
	s_barrier
	v_mfma_f32_16x16x32_bf16 v[54:57], v[148:151], v[188:191], v[54:57]
	v_mfma_f32_16x16x32_bf16 v[50:53], v[162:165], v[188:191], v[50:53]
	v_mfma_f32_16x16x32_bf16 v[38:41], v[148:151], v[196:199], v[38:41]
	v_mfma_f32_16x16x32_bf16 v[34:37], v[162:165], v[196:199], v[34:37]
	v_mfma_f32_16x16x32_bf16 v[22:25], v[148:151], v[204:207], v[22:25]
	v_mfma_f32_16x16x32_bf16 v[18:21], v[162:165], v[204:207], v[18:21]
	v_mfma_f32_16x16x32_bf16 v[6:9], v[148:151], v[212:215], v[6:9]
	v_mfma_f32_16x16x32_bf16 v[2:5], v[162:165], v[212:215], v[2:5]
	v_mfma_f32_16x16x32_bf16 v[54:57], v[158:161], v[192:195], v[54:57]
	v_mfma_f32_16x16x32_bf16 v[50:53], v[166:169], v[192:195], v[50:53]
	v_mfma_f32_16x16x32_bf16 v[38:41], v[158:161], v[200:203], v[38:41]
	v_mfma_f32_16x16x32_bf16 v[34:37], v[166:169], v[200:203], v[34:37]
	v_mfma_f32_16x16x32_bf16 v[22:25], v[158:161], v[208:211], v[22:25]
	v_mfma_f32_16x16x32_bf16 v[18:21], v[166:169], v[208:211], v[18:21]
	v_mfma_f32_16x16x32_bf16 v[6:9], v[158:161], v[216:219], v[6:9]
	v_mfma_f32_16x16x32_bf16 v[2:5], v[166:169], v[216:219], v[2:5]
	v_mfma_f32_16x16x32_bf16 v[62:65], v[170:173], v[188:191], v[62:65]
	v_mfma_f32_16x16x32_bf16 v[58:61], v[180:183], v[188:191], v[58:61]
	v_mfma_f32_16x16x32_bf16 v[46:49], v[170:173], v[196:199], v[46:49]
	v_mfma_f32_16x16x32_bf16 v[42:45], v[180:183], v[196:199], v[42:45]
	v_mfma_f32_16x16x32_bf16 v[30:33], v[170:173], v[204:207], v[30:33]
	v_mfma_f32_16x16x32_bf16 v[26:29], v[180:183], v[204:207], v[26:29]
	v_mfma_f32_16x16x32_bf16 v[14:17], v[170:173], v[212:215], v[14:17]
	v_mfma_f32_16x16x32_bf16 v[10:13], v[180:183], v[212:215], v[10:13]
	v_mfma_f32_16x16x32_bf16 v[62:65], v[174:177], v[192:195], v[62:65]
	v_mfma_f32_16x16x32_bf16 v[58:61], v[184:187], v[192:195], v[58:61]
	v_mfma_f32_16x16x32_bf16 v[46:49], v[174:177], v[200:203], v[46:49]
	v_mfma_f32_16x16x32_bf16 v[42:45], v[184:187], v[200:203], v[42:45]
	v_mfma_f32_16x16x32_bf16 v[30:33], v[174:177], v[208:211], v[30:33]
	v_mfma_f32_16x16x32_bf16 v[26:29], v[184:187], v[208:211], v[26:29]
	v_mfma_f32_16x16x32_bf16 v[14:17], v[174:177], v[216:219], v[14:17]
	v_mfma_f32_16x16x32_bf16 v[10:13], v[184:187], v[216:219], v[10:13]
	s_barrier
	s_setprio 0
	s_add_i32 s51, 0, 0x18000
	s_add_i32 s56, 0, 0x1c000
	v_add_u32_e32 v166, s51, v153
	v_add_u32_e32 v179, s56, v153
	ds_read_b128 v[148:151], v166
	ds_read_b128 v[158:161], v166 offset:1024
	ds_read_b128 v[162:165], v166 offset:2048
	ds_read_b128 v[166:169], v166 offset:3072
	ds_read_b128 v[170:173], v179
	ds_read_b128 v[174:177], v179 offset:1024
	ds_read_b128 v[180:183], v179 offset:2048
	ds_read_b128 v[184:187], v179 offset:3072
	s_add_u32 s28, s28, 0x40000
	s_addc_u32 s29, s29, 0
	s_mov_b32 m0, s35
	v_lshl_add_u64 v[228:229], s[28:29], 0, v[136:137]
	ds_read_b128 v[188:191], v157 offset:32768
	ds_read_b128 v[192:195], v157 offset:33792
	ds_read_b128 v[196:199], v157 offset:34816
	ds_read_b128 v[200:203], v157 offset:35840
	ds_read_b128 v[204:207], v157 offset:36864
	ds_read_b128 v[208:211], v157 offset:37888
	ds_read_b128 v[212:215], v157 offset:38912
	ds_read_b128 v[216:219], v157 offset:39936
	global_load_lds_dwordx4 v[228:229], off
	v_lshl_add_u64 v[228:229], s[28:29], 0, v[132:133]
	s_mov_b32 m0, s36
	s_nop 0
	global_load_lds_dwordx4 v[228:229], off
	s_waitcnt vmcnt(8)
	s_waitcnt lgkmcnt(0)
	s_setprio 1
	s_barrier
	v_mfma_f32_16x16x32_bf16 v[118:121], v[148:151], v[188:191], v[118:121]
	v_mfma_f32_16x16x32_bf16 v[114:117], v[162:165], v[188:191], v[114:117]
	v_mfma_f32_16x16x32_bf16 v[102:105], v[148:151], v[196:199], v[102:105]
	v_mfma_f32_16x16x32_bf16 v[98:101], v[162:165], v[196:199], v[98:101]
	v_mfma_f32_16x16x32_bf16 v[86:89], v[148:151], v[204:207], v[86:89]
	v_mfma_f32_16x16x32_bf16 v[82:85], v[162:165], v[204:207], v[82:85]
	v_mfma_f32_16x16x32_bf16 v[70:73], v[148:151], v[212:215], v[70:73]
	v_mfma_f32_16x16x32_bf16 v[66:69], v[162:165], v[212:215], v[66:69]
	v_mfma_f32_16x16x32_bf16 v[118:121], v[158:161], v[192:195], v[118:121]
	v_mfma_f32_16x16x32_bf16 v[114:117], v[166:169], v[192:195], v[114:117]
	v_mfma_f32_16x16x32_bf16 v[102:105], v[158:161], v[200:203], v[102:105]
	v_mfma_f32_16x16x32_bf16 v[98:101], v[166:169], v[200:203], v[98:101]
	v_mfma_f32_16x16x32_bf16 v[86:89], v[158:161], v[208:211], v[86:89]
	v_mfma_f32_16x16x32_bf16 v[82:85], v[166:169], v[208:211], v[82:85]
	v_mfma_f32_16x16x32_bf16 v[70:73], v[158:161], v[216:219], v[70:73]
	v_mfma_f32_16x16x32_bf16 v[66:69], v[166:169], v[216:219], v[66:69]
	v_mfma_f32_16x16x32_bf16 v[126:129], v[170:173], v[188:191], v[126:129]
	v_mfma_f32_16x16x32_bf16 v[122:125], v[180:183], v[188:191], v[122:125]
	v_mfma_f32_16x16x32_bf16 v[110:113], v[170:173], v[196:199], v[110:113]
	v_mfma_f32_16x16x32_bf16 v[106:109], v[180:183], v[196:199], v[106:109]
	v_mfma_f32_16x16x32_bf16 v[94:97], v[170:173], v[204:207], v[94:97]
	v_mfma_f32_16x16x32_bf16 v[90:93], v[180:183], v[204:207], v[90:93]
	v_mfma_f32_16x16x32_bf16 v[78:81], v[170:173], v[212:215], v[78:81]
	v_mfma_f32_16x16x32_bf16 v[74:77], v[180:183], v[212:215], v[74:77]
	v_mfma_f32_16x16x32_bf16 v[126:129], v[174:177], v[192:195], v[126:129]
	v_mfma_f32_16x16x32_bf16 v[122:125], v[184:187], v[192:195], v[122:125]
	v_mfma_f32_16x16x32_bf16 v[110:113], v[174:177], v[200:203], v[110:113]
	v_mfma_f32_16x16x32_bf16 v[106:109], v[184:187], v[200:203], v[106:109]
	v_mfma_f32_16x16x32_bf16 v[94:97], v[174:177], v[208:211], v[94:97]
	v_mfma_f32_16x16x32_bf16 v[90:93], v[184:187], v[208:211], v[90:93]
	v_mfma_f32_16x16x32_bf16 v[78:81], v[174:177], v[216:219], v[78:81]
	v_mfma_f32_16x16x32_bf16 v[74:77], v[184:187], v[216:219], v[74:77]
	s_barrier
	s_setprio 0
	s_add_i32 s28, s51, s30
	v_lshl_add_u64 v[220:221], v[220:221], 0, s[2:3]
	s_mov_b32 m0, s28
	ds_read_b128 v[188:191], v157 offset:49152
	ds_read_b128 v[192:195], v157 offset:50176
	ds_read_b128 v[196:199], v157 offset:51200
	ds_read_b128 v[200:203], v157 offset:52224
	ds_read_b128 v[204:207], v157 offset:53248
	ds_read_b128 v[208:211], v157 offset:54272
	ds_read_b128 v[212:215], v157 offset:55296
	ds_read_b128 v[216:219], v157 offset:56320
	global_load_lds_dwordx4 v[220:221], off
	s_add_i32 m0, s28, 0x2000
	s_add_u32 s26, s26, 0x40080
	v_lshl_add_u64 v[220:221], v[222:223], 0, s[2:3]
	s_addc_u32 s27, s27, 0
	s_add_i32 s28, s56, s30
	global_load_lds_dwordx4 v[220:221], off
	v_lshl_add_u64 v[220:221], s[26:27], 0, v[134:135]
	s_mov_b32 m0, s28
	s_nop 0
	global_load_lds_dwordx4 v[220:221], off
	v_lshl_add_u64 v[220:221], s[26:27], 0, v[130:131]
	s_add_i32 m0, s28, 0x2000
	s_nop 0
	global_load_lds_dwordx4 v[220:221], off
	v_lshl_add_u64 v[220:221], v[224:225], 0, s[2:3]
	s_mov_b32 m0, s38
	s_nop 0
	global_load_lds_dwordx4 v[220:221], off
	v_lshl_add_u64 v[220:221], v[226:227], 0, s[2:3]
	s_mov_b32 m0, s39
	s_nop 0
	global_load_lds_dwordx4 v[220:221], off
	s_waitcnt vmcnt(8)
	s_waitcnt lgkmcnt(0)
	s_nop 0
	s_setprio 1
	s_barrier
	v_mfma_f32_16x16x32_bf16 v[54:57], v[148:151], v[188:191], v[54:57]
	v_mfma_f32_16x16x32_bf16 v[50:53], v[162:165], v[188:191], v[50:53]
	v_mfma_f32_16x16x32_bf16 v[38:41], v[148:151], v[196:199], v[38:41]
	v_mfma_f32_16x16x32_bf16 v[34:37], v[162:165], v[196:199], v[34:37]
	v_mfma_f32_16x16x32_bf16 v[22:25], v[148:151], v[204:207], v[22:25]
	v_mfma_f32_16x16x32_bf16 v[18:21], v[162:165], v[204:207], v[18:21]
	v_mfma_f32_16x16x32_bf16 v[6:9], v[148:151], v[212:215], v[6:9]
	v_mfma_f32_16x16x32_bf16 v[2:5], v[162:165], v[212:215], v[2:5]
	v_mfma_f32_16x16x32_bf16 v[54:57], v[158:161], v[192:195], v[54:57]
	v_mfma_f32_16x16x32_bf16 v[50:53], v[166:169], v[192:195], v[50:53]
	v_mfma_f32_16x16x32_bf16 v[38:41], v[158:161], v[200:203], v[38:41]
	v_mfma_f32_16x16x32_bf16 v[34:37], v[166:169], v[200:203], v[34:37]
	v_mfma_f32_16x16x32_bf16 v[22:25], v[158:161], v[208:211], v[22:25]
	v_mfma_f32_16x16x32_bf16 v[18:21], v[166:169], v[208:211], v[18:21]
	v_mfma_f32_16x16x32_bf16 v[6:9], v[158:161], v[216:219], v[6:9]
	v_mfma_f32_16x16x32_bf16 v[2:5], v[166:169], v[216:219], v[2:5]
	v_mfma_f32_16x16x32_bf16 v[62:65], v[170:173], v[188:191], v[62:65]
	v_mfma_f32_16x16x32_bf16 v[58:61], v[180:183], v[188:191], v[58:61]
	v_mfma_f32_16x16x32_bf16 v[46:49], v[170:173], v[196:199], v[46:49]
	v_mfma_f32_16x16x32_bf16 v[42:45], v[180:183], v[196:199], v[42:45]
	v_mfma_f32_16x16x32_bf16 v[30:33], v[170:173], v[204:207], v[30:33]
	v_mfma_f32_16x16x32_bf16 v[26:29], v[180:183], v[204:207], v[26:29]
	v_mfma_f32_16x16x32_bf16 v[14:17], v[170:173], v[212:215], v[14:17]
	v_mfma_f32_16x16x32_bf16 v[10:13], v[180:183], v[212:215], v[10:13]
	v_mfma_f32_16x16x32_bf16 v[62:65], v[174:177], v[192:195], v[62:65]
	v_mfma_f32_16x16x32_bf16 v[58:61], v[184:187], v[192:195], v[58:61]
	v_mfma_f32_16x16x32_bf16 v[46:49], v[174:177], v[200:203], v[46:49]
	v_mfma_f32_16x16x32_bf16 v[42:45], v[184:187], v[200:203], v[42:45]
	v_mfma_f32_16x16x32_bf16 v[30:33], v[174:177], v[208:211], v[30:33]
	v_mfma_f32_16x16x32_bf16 v[26:29], v[184:187], v[208:211], v[26:29]
	v_mfma_f32_16x16x32_bf16 v[14:17], v[174:177], v[216:219], v[14:17]
	v_mfma_f32_16x16x32_bf16 v[10:13], v[184:187], v[216:219], v[10:13]
	s_barrier
	s_setprio 0
	s_add_i32 s50, s50, 2
	s_add_u32 s24, s24, 0x100
	s_addc_u32 s25, s25, 0
	s_add_u32 s48, s48, 0x100
	s_addc_u32 s49, s49, 0
	s_cmp_gt_u32 s50, 13
	s_cbranch_scc0 .LBB0_1054
	s_and_b64 vcc, exec, s[8:9]
	s_cbranch_vccz .LBB0_1057
	s_barrier

.LBB0_1124:
	ds_read_b128 v[86:89], v182
	ds_read_b128 v[90:93], v182 offset:1024
	ds_read_b128 v[98:101], v182 offset:2048
	ds_read_b128 v[102:105], v182 offset:3072
	ds_read_b128 v[164:167], v183
	ds_read_b128 v[168:171], v183 offset:1024
	ds_read_b128 v[172:175], v183 offset:2048
	ds_read_b128 v[186:189], v183 offset:3072
	s_add_u32 s34, s30, 0xfff80080
	s_addc_u32 s35, s31, -1
	s_cmp_eq_u32 s59, 28
	s_cselect_b32 s37, s21, s35
	s_cselect_b32 s36, s27, s34
	s_cselect_b32 s35, s19, s58
	s_cselect_b32 s34, s29, s57
	v_lshl_add_u64 v[176:177], s[30:31], 0, v[156:157]
	s_add_i32 m0, s38, 0xc000
	ds_read_b128 v[190:193], v184
	ds_read_b128 v[194:197], v184 offset:1024
	ds_read_b128 v[198:201], v184 offset:2048
	ds_read_b128 v[202:205], v184 offset:3072
	ds_read_b128 v[206:209], v184 offset:4096
	ds_read_b128 v[210:213], v184 offset:5120
	ds_read_b128 v[214:217], v184 offset:6144
	ds_read_b128 v[218:221], v184 offset:7168
	global_load_lds_dwordx4 v[176:177], off
	v_lshl_add_u64 v[176:177], s[30:31], 0, v[158:159]
	s_add_i32 m0, s38, 0xe000
	s_nop 0
	global_load_lds_dwordx4 v[176:177], off
	s_waitcnt vmcnt(8)
	s_waitcnt lgkmcnt(0)
	s_setprio 1
	s_barrier
	v_mfma_f32_16x16x32_bf16 v[142:145], v[86:89], v[190:193], v[142:145]
	v_mfma_f32_16x16x32_bf16 v[138:141], v[98:101], v[190:193], v[138:141]
	v_mfma_f32_16x16x32_bf16 v[126:129], v[86:89], v[198:201], v[126:129]
	v_mfma_f32_16x16x32_bf16 v[122:125], v[98:101], v[198:201], v[122:125]
	v_mfma_f32_16x16x32_bf16 v[110:113], v[86:89], v[206:209], v[110:113]
	v_mfma_f32_16x16x32_bf16 v[106:109], v[98:101], v[206:209], v[106:109]
	v_mfma_f32_16x16x32_bf16 v[78:81], v[86:89], v[214:217], v[78:81]
	v_mfma_f32_16x16x32_bf16 v[74:77], v[98:101], v[214:217], v[74:77]
	v_mfma_f32_16x16x32_bf16 v[142:145], v[90:93], v[194:197], v[142:145]
	v_mfma_f32_16x16x32_bf16 v[138:141], v[102:105], v[194:197], v[138:141]
	v_mfma_f32_16x16x32_bf16 v[126:129], v[90:93], v[202:205], v[126:129]
	v_mfma_f32_16x16x32_bf16 v[122:125], v[102:105], v[202:205], v[122:125]
	v_mfma_f32_16x16x32_bf16 v[110:113], v[90:93], v[210:213], v[110:113]
	v_mfma_f32_16x16x32_bf16 v[106:109], v[102:105], v[210:213], v[106:109]
	v_mfma_f32_16x16x32_bf16 v[78:81], v[90:93], v[218:221], v[78:81]
	v_mfma_f32_16x16x32_bf16 v[74:77], v[102:105], v[218:221], v[74:77]
	v_mfma_f32_16x16x32_bf16 v[134:137], v[164:167], v[190:193], v[134:137]
	v_mfma_f32_16x16x32_bf16 v[130:133], v[172:175], v[190:193], v[130:133]
	v_mfma_f32_16x16x32_bf16 v[118:121], v[164:167], v[198:201], v[118:121]
	v_mfma_f32_16x16x32_bf16 v[114:117], v[172:175], v[198:201], v[114:117]
	v_mfma_f32_16x16x32_bf16 v[94:97], v[164:167], v[206:209], v[94:97]
	v_mfma_f32_16x16x32_bf16 v[82:85], v[172:175], v[206:209], v[82:85]
	v_mfma_f32_16x16x32_bf16 v[70:73], v[164:167], v[214:217], v[70:73]
	v_mfma_f32_16x16x32_bf16 v[66:69], v[172:175], v[214:217], v[66:69]
	v_mfma_f32_16x16x32_bf16 v[134:137], v[168:171], v[194:197], v[134:137]
	v_mfma_f32_16x16x32_bf16 v[130:133], v[186:189], v[194:197], v[130:133]
	v_mfma_f32_16x16x32_bf16 v[118:121], v[168:171], v[202:205], v[118:121]
	v_mfma_f32_16x16x32_bf16 v[114:117], v[186:189], v[202:205], v[114:117]
	v_mfma_f32_16x16x32_bf16 v[94:97], v[168:171], v[210:213], v[94:97]
	v_mfma_f32_16x16x32_bf16 v[82:85], v[186:189], v[210:213], v[82:85]
	v_mfma_f32_16x16x32_bf16 v[70:73], v[168:171], v[218:221], v[70:73]
	v_mfma_f32_16x16x32_bf16 v[66:69], v[186:189], v[218:221], v[66:69]
	s_barrier
	s_setprio 0
	s_add_i32 s68, s51, s33
	v_lshl_add_u64 v[176:177], s[34:35], 0, v[150:151]
	s_mov_b32 m0, s68
	ds_read_b128 v[190:193], v184 offset:16384
	ds_read_b128 v[194:197], v184 offset:17408
	ds_read_b128 v[198:201], v184 offset:18432
	ds_read_b128 v[202:205], v184 offset:19456
	ds_read_b128 v[206:209], v184 offset:20480
	ds_read_b128 v[210:213], v184 offset:21504
	ds_read_b128 v[214:217], v184 offset:22528
	ds_read_b128 v[218:221], v184 offset:23552
	global_load_lds_dwordx4 v[176:177], off
	s_add_i32 m0, s68, 0x2000
	s_add_u32 s68, s34, 0x80000
	v_lshl_add_u64 v[222:223], s[34:35], 0, v[154:155]
	s_addc_u32 s69, s35, 0
	s_add_i32 s70, s56, s33
	global_load_lds_dwordx4 v[222:223], off
	v_lshl_add_u64 v[224:225], s[68:69], 0, v[150:151]
	s_mov_b32 m0, s70
	v_lshl_add_u64 v[226:227], s[36:37], 0, v[152:153]
	global_load_lds_dwordx4 v[224:225], off
	v_lshl_add_u64 v[224:225], s[68:69], 0, v[154:155]
	s_add_i32 m0, s70, 0x2000
	s_nop 0
	global_load_lds_dwordx4 v[224:225], off
	v_lshl_add_u64 v[224:225], s[36:37], 0, v[148:149]
	s_mov_b32 m0, s38
	s_nop 0
	global_load_lds_dwordx4 v[224:225], off
	s_mov_b32 m0, s39
	s_nop 0
	global_load_lds_dwordx4 v[226:227], off
	s_waitcnt vmcnt(8)
	s_waitcnt lgkmcnt(0)
	s_setprio 1
	s_barrier
	v_mfma_f32_16x16x32_bf16 v[62:65], v[86:89], v[190:193], v[62:65]
	v_mfma_f32_16x16x32_bf16 v[58:61], v[98:101], v[190:193], v[58:61]
	v_mfma_f32_16x16x32_bf16 v[46:49], v[86:89], v[198:201], v[46:49]
	v_mfma_f32_16x16x32_bf16 v[42:45], v[98:101], v[198:201], v[42:45]
	v_mfma_f32_16x16x32_bf16 v[30:33], v[86:89], v[206:209], v[30:33]
	v_mfma_f32_16x16x32_bf16 v[26:29], v[98:101], v[206:209], v[26:29]
	v_mfma_f32_16x16x32_bf16 v[14:17], v[86:89], v[214:217], v[14:17]
	v_mfma_f32_16x16x32_bf16 v[10:13], v[98:101], v[214:217], v[10:13]
	v_mfma_f32_16x16x32_bf16 v[62:65], v[90:93], v[194:197], v[62:65]
	v_mfma_f32_16x16x32_bf16 v[58:61], v[102:105], v[194:197], v[58:61]
	v_mfma_f32_16x16x32_bf16 v[46:49], v[90:93], v[202:205], v[46:49]
	v_mfma_f32_16x16x32_bf16 v[42:45], v[102:105], v[202:205], v[42:45]
	v_mfma_f32_16x16x32_bf16 v[30:33], v[90:93], v[210:213], v[30:33]
	v_mfma_f32_16x16x32_bf16 v[26:29], v[102:105], v[210:213], v[26:29]
	v_mfma_f32_16x16x32_bf16 v[14:17], v[90:93], v[218:221], v[14:17]
	v_mfma_f32_16x16x32_bf16 v[10:13], v[102:105], v[218:221], v[10:13]
	v_mfma_f32_16x16x32_bf16 v[54:57], v[164:167], v[190:193], v[54:57]
	v_mfma_f32_16x16x32_bf16 v[50:53], v[172:175], v[190:193], v[50:53]
	v_mfma_f32_16x16x32_bf16 v[38:41], v[164:167], v[198:201], v[38:41]
	v_mfma_f32_16x16x32_bf16 v[34:37], v[172:175], v[198:201], v[34:37]
	v_mfma_f32_16x16x32_bf16 v[22:25], v[164:167], v[206:209], v[22:25]
	v_mfma_f32_16x16x32_bf16 v[18:21], v[172:175], v[206:209], v[18:21]
	v_mfma_f32_16x16x32_bf16 v[6:9], v[164:167], v[214:217], v[6:9]
	v_mfma_f32_16x16x32_bf16 v[2:5], v[172:175], v[214:217], v[2:5]
	v_mfma_f32_16x16x32_bf16 v[54:57], v[168:171], v[194:197], v[54:57]
	v_mfma_f32_16x16x32_bf16 v[50:53], v[186:189], v[194:197], v[50:53]
	v_mfma_f32_16x16x32_bf16 v[38:41], v[168:171], v[202:205], v[38:41]
	v_mfma_f32_16x16x32_bf16 v[34:37], v[186:189], v[202:205], v[34:37]
	v_mfma_f32_16x16x32_bf16 v[22:25], v[168:171], v[210:213], v[22:25]
	v_mfma_f32_16x16x32_bf16 v[18:21], v[186:189], v[210:213], v[18:21]
	v_mfma_f32_16x16x32_bf16 v[6:9], v[168:171], v[218:221], v[6:9]
	v_mfma_f32_16x16x32_bf16 v[2:5], v[186:189], v[218:221], v[2:5]
	s_barrier
	s_setprio 0
	s_add_i32 s68, 0, 0x18000
	s_add_i32 s69, 0, 0x1c000
	v_add_u32_e32 v102, s68, v180
	v_add_u32_e32 v185, s69, v180
	ds_read_b128 v[86:89], v102
	ds_read_b128 v[90:93], v102 offset:1024
	ds_read_b128 v[98:101], v102 offset:2048
	ds_read_b128 v[102:105], v102 offset:3072
	ds_read_b128 v[164:167], v185
	ds_read_b128 v[168:171], v185 offset:1024
	ds_read_b128 v[172:175], v185 offset:2048
	ds_read_b128 v[186:189], v185 offset:3072
	s_add_u32 s36, s36, 0x80000
	s_addc_u32 s37, s37, 0
	s_mov_b32 m0, s40
	v_lshl_add_u64 v[228:229], s[36:37], 0, v[148:149]
	ds_read_b128 v[190:193], v184 offset:32768
	ds_read_b128 v[194:197], v184 offset:33792
	ds_read_b128 v[198:201], v184 offset:34816
	ds_read_b128 v[202:205], v184 offset:35840
	ds_read_b128 v[206:209], v184 offset:36864
	ds_read_b128 v[210:213], v184 offset:37888
	ds_read_b128 v[214:217], v184 offset:38912
	ds_read_b128 v[218:221], v184 offset:39936
	global_load_lds_dwordx4 v[228:229], off
	v_lshl_add_u64 v[228:229], s[36:37], 0, v[152:153]
	s_mov_b32 m0, s41
	s_nop 0
	global_load_lds_dwordx4 v[228:229], off
	s_waitcnt vmcnt(8)
	s_waitcnt lgkmcnt(0)
	s_setprio 1
	s_barrier
	v_mfma_f32_16x16x32_bf16 v[142:145], v[86:89], v[190:193], v[142:145]
	v_mfma_f32_16x16x32_bf16 v[138:141], v[98:101], v[190:193], v[138:141]
	v_mfma_f32_16x16x32_bf16 v[126:129], v[86:89], v[198:201], v[126:129]
	v_mfma_f32_16x16x32_bf16 v[122:125], v[98:101], v[198:201], v[122:125]
	v_mfma_f32_16x16x32_bf16 v[110:113], v[86:89], v[206:209], v[110:113]
	v_mfma_f32_16x16x32_bf16 v[106:109], v[98:101], v[206:209], v[106:109]
	v_mfma_f32_16x16x32_bf16 v[78:81], v[86:89], v[214:217], v[78:81]
	v_mfma_f32_16x16x32_bf16 v[74:77], v[98:101], v[214:217], v[74:77]
	v_mfma_f32_16x16x32_bf16 v[142:145], v[90:93], v[194:197], v[142:145]
	v_mfma_f32_16x16x32_bf16 v[138:141], v[102:105], v[194:197], v[138:141]
	v_mfma_f32_16x16x32_bf16 v[126:129], v[90:93], v[202:205], v[126:129]
	v_mfma_f32_16x16x32_bf16 v[122:125], v[102:105], v[202:205], v[122:125]
	v_mfma_f32_16x16x32_bf16 v[110:113], v[90:93], v[210:213], v[110:113]
	v_mfma_f32_16x16x32_bf16 v[106:109], v[102:105], v[210:213], v[106:109]
	v_mfma_f32_16x16x32_bf16 v[78:81], v[90:93], v[218:221], v[78:81]
	v_mfma_f32_16x16x32_bf16 v[74:77], v[102:105], v[218:221], v[74:77]
	v_mfma_f32_16x16x32_bf16 v[134:137], v[164:167], v[190:193], v[134:137]
	v_mfma_f32_16x16x32_bf16 v[130:133], v[172:175], v[190:193], v[130:133]
	v_mfma_f32_16x16x32_bf16 v[118:121], v[164:167], v[198:201], v[118:121]
	v_mfma_f32_16x16x32_bf16 v[114:117], v[172:175], v[198:201], v[114:117]
	v_mfma_f32_16x16x32_bf16 v[94:97], v[164:167], v[206:209], v[94:97]
	v_mfma_f32_16x16x32_bf16 v[82:85], v[172:175], v[206:209], v[82:85]
	v_mfma_f32_16x16x32_bf16 v[70:73], v[164:167], v[214:217], v[70:73]
	v_mfma_f32_16x16x32_bf16 v[66:69], v[172:175], v[214:217], v[66:69]
	v_mfma_f32_16x16x32_bf16 v[134:137], v[168:171], v[194:197], v[134:137]
	v_mfma_f32_16x16x32_bf16 v[130:133], v[186:189], v[194:197], v[130:133]
	v_mfma_f32_16x16x32_bf16 v[118:121], v[168:171], v[202:205], v[118:121]
	v_mfma_f32_16x16x32_bf16 v[114:117], v[186:189], v[202:205], v[114:117]
	v_mfma_f32_16x16x32_bf16 v[94:97], v[168:171], v[210:213], v[94:97]
	v_mfma_f32_16x16x32_bf16 v[82:85], v[186:189], v[210:213], v[82:85]
	v_mfma_f32_16x16x32_bf16 v[70:73], v[168:171], v[218:221], v[70:73]
	v_mfma_f32_16x16x32_bf16 v[66:69], v[186:189], v[218:221], v[66:69]
	s_barrier
	s_setprio 0
	s_add_i32 s36, s68, s33
	v_lshl_add_u64 v[176:177], v[176:177], 0, s[2:3]
	s_mov_b32 m0, s36
	ds_read_b128 v[190:193], v184 offset:49152
	ds_read_b128 v[194:197], v184 offset:50176
	ds_read_b128 v[198:201], v184 offset:51200
	ds_read_b128 v[202:205], v184 offset:52224
	ds_read_b128 v[206:209], v184 offset:53248
	ds_read_b128 v[210:213], v184 offset:54272
	ds_read_b128 v[214:217], v184 offset:55296
	ds_read_b128 v[218:221], v184 offset:56320
	global_load_lds_dwordx4 v[176:177], off
	s_add_i32 m0, s36, 0x2000
	s_add_u32 s34, s34, 0x80080
	v_lshl_add_u64 v[176:177], v[222:223], 0, s[2:3]
	s_addc_u32 s35, s35, 0
	s_add_i32 s36, s69, s33
	global_load_lds_dwordx4 v[176:177], off
	v_lshl_add_u64 v[176:177], s[34:35], 0, v[150:151]
	s_mov_b32 m0, s36
	s_nop 0
	global_load_lds_dwordx4 v[176:177], off
	v_lshl_add_u64 v[176:177], s[34:35], 0, v[154:155]
	s_add_i32 m0, s36, 0x2000
	s_nop 0
	global_load_lds_dwordx4 v[176:177], off
	v_lshl_add_u64 v[176:177], v[224:225], 0, s[2:3]
	s_mov_b32 m0, s43
	s_nop 0
	global_load_lds_dwordx4 v[176:177], off
	v_lshl_add_u64 v[176:177], v[226:227], 0, s[2:3]
	s_mov_b32 m0, s44
	s_nop 0
	global_load_lds_dwordx4 v[176:177], off
	s_waitcnt vmcnt(8)
	s_waitcnt lgkmcnt(0)
	s_nop 0
	s_setprio 1
	s_barrier
	v_mfma_f32_16x16x32_bf16 v[62:65], v[86:89], v[190:193], v[62:65]
	v_mfma_f32_16x16x32_bf16 v[58:61], v[98:101], v[190:193], v[58:61]
	v_mfma_f32_16x16x32_bf16 v[46:49], v[86:89], v[198:201], v[46:49]
	v_mfma_f32_16x16x32_bf16 v[42:45], v[98:101], v[198:201], v[42:45]
	v_mfma_f32_16x16x32_bf16 v[30:33], v[86:89], v[206:209], v[30:33]
	v_mfma_f32_16x16x32_bf16 v[26:29], v[98:101], v[206:209], v[26:29]
	v_mfma_f32_16x16x32_bf16 v[14:17], v[86:89], v[214:217], v[14:17]
	v_mfma_f32_16x16x32_bf16 v[10:13], v[98:101], v[214:217], v[10:13]
	v_mfma_f32_16x16x32_bf16 v[62:65], v[90:93], v[194:197], v[62:65]
	v_mfma_f32_16x16x32_bf16 v[58:61], v[102:105], v[194:197], v[58:61]
	v_mfma_f32_16x16x32_bf16 v[46:49], v[90:93], v[202:205], v[46:49]
	v_mfma_f32_16x16x32_bf16 v[42:45], v[102:105], v[202:205], v[42:45]
	v_mfma_f32_16x16x32_bf16 v[30:33], v[90:93], v[210:213], v[30:33]
	v_mfma_f32_16x16x32_bf16 v[26:29], v[102:105], v[210:213], v[26:29]
	v_mfma_f32_16x16x32_bf16 v[14:17], v[90:93], v[218:221], v[14:17]
	v_mfma_f32_16x16x32_bf16 v[10:13], v[102:105], v[218:221], v[10:13]
	v_mfma_f32_16x16x32_bf16 v[54:57], v[164:167], v[190:193], v[54:57]
	v_mfma_f32_16x16x32_bf16 v[50:53], v[172:175], v[190:193], v[50:53]
	v_mfma_f32_16x16x32_bf16 v[38:41], v[164:167], v[198:201], v[38:41]
	v_mfma_f32_16x16x32_bf16 v[34:37], v[172:175], v[198:201], v[34:37]
	v_mfma_f32_16x16x32_bf16 v[22:25], v[164:167], v[206:209], v[22:25]
	v_mfma_f32_16x16x32_bf16 v[18:21], v[172:175], v[206:209], v[18:21]
	v_mfma_f32_16x16x32_bf16 v[6:9], v[164:167], v[214:217], v[6:9]
	v_mfma_f32_16x16x32_bf16 v[2:5], v[172:175], v[214:217], v[2:5]
	v_mfma_f32_16x16x32_bf16 v[54:57], v[168:171], v[194:197], v[54:57]
	v_mfma_f32_16x16x32_bf16 v[50:53], v[186:189], v[194:197], v[50:53]
	v_mfma_f32_16x16x32_bf16 v[38:41], v[168:171], v[202:205], v[38:41]
	v_mfma_f32_16x16x32_bf16 v[34:37], v[186:189], v[202:205], v[34:37]
	v_mfma_f32_16x16x32_bf16 v[22:25], v[168:171], v[210:213], v[22:25]
	v_mfma_f32_16x16x32_bf16 v[18:21], v[186:189], v[210:213], v[18:21]
	v_mfma_f32_16x16x32_bf16 v[6:9], v[168:171], v[218:221], v[6:9]
	v_mfma_f32_16x16x32_bf16 v[2:5], v[186:189], v[218:221], v[2:5]
	s_barrier
	s_setprio 0
	s_add_i32 s59, s59, 2
	s_add_u32 s30, s30, 0x100
	s_addc_u32 s31, s31, 0
	s_add_u32 s57, s57, 0x100
	s_addc_u32 s58, s58, 0
	s_cmp_gt_u32 s59, 29
	s_cbranch_scc0 .LBB0_1124
	s_and_b64 vcc, exec, s[16:17]
	s_cbranch_vccz .LBB0_1127
	s_barrier

.LBB0_1208:
	ds_read_b128 v[98:101], v175
	ds_read_b128 v[102:105], v175 offset:1024
	ds_read_b128 v[106:109], v175 offset:2048
	ds_read_b128 v[110:113], v175 offset:3072
	ds_read_b128 v[164:167], v176
	ds_read_b128 v[168:171], v176 offset:1024
	ds_read_b128 v[182:185], v176 offset:2048
	ds_read_b128 v[186:189], v176 offset:3072
	s_add_u32 s28, s26, 0xfff80080
	s_addc_u32 s29, s27, -1
	s_cmp_eq_u32 s58, 28
	s_cselect_b32 s31, s21, s29
	s_cselect_b32 s30, s50, s28
	s_cselect_b32 s29, s19, s57
	s_cselect_b32 s28, s51, s56
	v_lshl_add_u64 v[222:223], s[26:27], 0, v[156:157]
	s_add_i32 m0, s36, 0xc000
	ds_read_b128 v[190:193], v177
	ds_read_b128 v[194:197], v177 offset:1024
	ds_read_b128 v[198:201], v177 offset:2048
	ds_read_b128 v[202:205], v177 offset:3072
	ds_read_b128 v[206:209], v177 offset:4096
	ds_read_b128 v[210:213], v177 offset:5120
	ds_read_b128 v[214:217], v177 offset:6144
	ds_read_b128 v[218:221], v177 offset:7168
	global_load_lds_dwordx4 v[222:223], off
	v_lshl_add_u64 v[222:223], s[26:27], 0, v[158:159]
	s_add_i32 m0, s36, 0xe000
	s_nop 0
	global_load_lds_dwordx4 v[222:223], off
	s_waitcnt vmcnt(8)
	s_waitcnt lgkmcnt(0)
	s_setprio 1
	s_barrier
	v_mfma_f32_16x16x32_bf16 v[142:145], v[98:101], v[190:193], v[142:145]
	v_mfma_f32_16x16x32_bf16 v[138:141], v[106:109], v[190:193], v[138:141]
	v_mfma_f32_16x16x32_bf16 v[126:129], v[98:101], v[198:201], v[126:129]
	v_mfma_f32_16x16x32_bf16 v[122:125], v[106:109], v[198:201], v[122:125]
	v_mfma_f32_16x16x32_bf16 v[94:97], v[98:101], v[206:209], v[94:97]
	v_mfma_f32_16x16x32_bf16 v[90:93], v[106:109], v[206:209], v[90:93]
	v_mfma_f32_16x16x32_bf16 v[78:81], v[98:101], v[214:217], v[78:81]
	v_mfma_f32_16x16x32_bf16 v[74:77], v[106:109], v[214:217], v[74:77]
	v_mfma_f32_16x16x32_bf16 v[142:145], v[102:105], v[194:197], v[142:145]
	v_mfma_f32_16x16x32_bf16 v[138:141], v[110:113], v[194:197], v[138:141]
	v_mfma_f32_16x16x32_bf16 v[126:129], v[102:105], v[202:205], v[126:129]
	v_mfma_f32_16x16x32_bf16 v[122:125], v[110:113], v[202:205], v[122:125]
	v_mfma_f32_16x16x32_bf16 v[94:97], v[102:105], v[210:213], v[94:97]
	v_mfma_f32_16x16x32_bf16 v[90:93], v[110:113], v[210:213], v[90:93]
	v_mfma_f32_16x16x32_bf16 v[78:81], v[102:105], v[218:221], v[78:81]
	v_mfma_f32_16x16x32_bf16 v[74:77], v[110:113], v[218:221], v[74:77]
	v_mfma_f32_16x16x32_bf16 v[134:137], v[164:167], v[190:193], v[134:137]
	v_mfma_f32_16x16x32_bf16 v[130:133], v[182:185], v[190:193], v[130:133]
	v_mfma_f32_16x16x32_bf16 v[118:121], v[164:167], v[198:201], v[118:121]
	v_mfma_f32_16x16x32_bf16 v[114:117], v[182:185], v[198:201], v[114:117]
	v_mfma_f32_16x16x32_bf16 v[86:89], v[164:167], v[206:209], v[86:89]
	v_mfma_f32_16x16x32_bf16 v[82:85], v[182:185], v[206:209], v[82:85]
	v_mfma_f32_16x16x32_bf16 v[70:73], v[164:167], v[214:217], v[70:73]
	v_mfma_f32_16x16x32_bf16 v[66:69], v[182:185], v[214:217], v[66:69]
	v_mfma_f32_16x16x32_bf16 v[134:137], v[168:171], v[194:197], v[134:137]
	v_mfma_f32_16x16x32_bf16 v[130:133], v[186:189], v[194:197], v[130:133]
	v_mfma_f32_16x16x32_bf16 v[118:121], v[168:171], v[202:205], v[118:121]
	v_mfma_f32_16x16x32_bf16 v[114:117], v[186:189], v[202:205], v[114:117]
	v_mfma_f32_16x16x32_bf16 v[86:89], v[168:171], v[210:213], v[86:89]
	v_mfma_f32_16x16x32_bf16 v[82:85], v[186:189], v[210:213], v[82:85]
	v_mfma_f32_16x16x32_bf16 v[70:73], v[168:171], v[218:221], v[70:73]
	v_mfma_f32_16x16x32_bf16 v[66:69], v[186:189], v[218:221], v[66:69]
	s_barrier
	s_setprio 0
	s_add_i32 s59, s45, s33
	v_lshl_add_u64 v[222:223], s[28:29], 0, v[152:153]
	s_mov_b32 m0, s59
	ds_read_b128 v[190:193], v177 offset:16384
	ds_read_b128 v[194:197], v177 offset:17408
	ds_read_b128 v[198:201], v177 offset:18432
	ds_read_b128 v[202:205], v177 offset:19456
	ds_read_b128 v[206:209], v177 offset:20480
	ds_read_b128 v[210:213], v177 offset:21504
	ds_read_b128 v[214:217], v177 offset:22528
	ds_read_b128 v[218:221], v177 offset:23552
	global_load_lds_dwordx4 v[222:223], off
	s_add_i32 m0, s59, 0x2000
	s_add_u32 s68, s28, 0x80000
	v_lshl_add_u64 v[224:225], s[28:29], 0, v[148:149]
	s_addc_u32 s69, s29, 0
	s_add_i32 s59, s46, s33
	global_load_lds_dwordx4 v[224:225], off
	v_lshl_add_u64 v[226:227], s[68:69], 0, v[152:153]
	s_mov_b32 m0, s59
	v_lshl_add_u64 v[228:229], s[30:31], 0, v[150:151]
	global_load_lds_dwordx4 v[226:227], off
	v_lshl_add_u64 v[226:227], s[68:69], 0, v[148:149]
	s_add_i32 m0, s59, 0x2000
	s_nop 0
	global_load_lds_dwordx4 v[226:227], off
	v_lshl_add_u64 v[226:227], s[30:31], 0, v[154:155]
	s_mov_b32 m0, s36
	s_nop 0
	global_load_lds_dwordx4 v[226:227], off
	s_mov_b32 m0, s37
	s_nop 0
	global_load_lds_dwordx4 v[228:229], off
	s_waitcnt vmcnt(8)
	s_waitcnt lgkmcnt(0)
	s_setprio 1
	s_barrier
	v_mfma_f32_16x16x32_bf16 v[62:65], v[98:101], v[190:193], v[62:65]
	v_mfma_f32_16x16x32_bf16 v[58:61], v[106:109], v[190:193], v[58:61]
	v_mfma_f32_16x16x32_bf16 v[46:49], v[98:101], v[198:201], v[46:49]
	v_mfma_f32_16x16x32_bf16 v[42:45], v[106:109], v[198:201], v[42:45]
	v_mfma_f32_16x16x32_bf16 v[30:33], v[98:101], v[206:209], v[30:33]
	v_mfma_f32_16x16x32_bf16 v[26:29], v[106:109], v[206:209], v[26:29]
	v_mfma_f32_16x16x32_bf16 v[14:17], v[98:101], v[214:217], v[14:17]
	v_mfma_f32_16x16x32_bf16 v[10:13], v[106:109], v[214:217], v[10:13]
	v_mfma_f32_16x16x32_bf16 v[62:65], v[102:105], v[194:197], v[62:65]
	v_mfma_f32_16x16x32_bf16 v[58:61], v[110:113], v[194:197], v[58:61]
	v_mfma_f32_16x16x32_bf16 v[46:49], v[102:105], v[202:205], v[46:49]
	v_mfma_f32_16x16x32_bf16 v[42:45], v[110:113], v[202:205], v[42:45]
	v_mfma_f32_16x16x32_bf16 v[30:33], v[102:105], v[210:213], v[30:33]
	v_mfma_f32_16x16x32_bf16 v[26:29], v[110:113], v[210:213], v[26:29]
	v_mfma_f32_16x16x32_bf16 v[14:17], v[102:105], v[218:221], v[14:17]
	v_mfma_f32_16x16x32_bf16 v[10:13], v[110:113], v[218:221], v[10:13]
	v_mfma_f32_16x16x32_bf16 v[54:57], v[164:167], v[190:193], v[54:57]
	v_mfma_f32_16x16x32_bf16 v[50:53], v[182:185], v[190:193], v[50:53]
	v_mfma_f32_16x16x32_bf16 v[38:41], v[164:167], v[198:201], v[38:41]
	v_mfma_f32_16x16x32_bf16 v[34:37], v[182:185], v[198:201], v[34:37]
	v_mfma_f32_16x16x32_bf16 v[22:25], v[164:167], v[206:209], v[22:25]
	v_mfma_f32_16x16x32_bf16 v[18:21], v[182:185], v[206:209], v[18:21]
	v_mfma_f32_16x16x32_bf16 v[6:9], v[164:167], v[214:217], v[6:9]
	v_mfma_f32_16x16x32_bf16 v[2:5], v[182:185], v[214:217], v[2:5]
	v_mfma_f32_16x16x32_bf16 v[54:57], v[168:171], v[194:197], v[54:57]
	v_mfma_f32_16x16x32_bf16 v[50:53], v[186:189], v[194:197], v[50:53]
	v_mfma_f32_16x16x32_bf16 v[38:41], v[168:171], v[202:205], v[38:41]
	v_mfma_f32_16x16x32_bf16 v[34:37], v[186:189], v[202:205], v[34:37]
	v_mfma_f32_16x16x32_bf16 v[22:25], v[168:171], v[210:213], v[22:25]
	v_mfma_f32_16x16x32_bf16 v[18:21], v[186:189], v[210:213], v[18:21]
	v_mfma_f32_16x16x32_bf16 v[6:9], v[168:171], v[218:221], v[6:9]
	v_mfma_f32_16x16x32_bf16 v[2:5], v[186:189], v[218:221], v[2:5]
	s_barrier
	s_setprio 0
	s_add_i32 s59, 0, 0x18000
	s_add_i32 s68, 0, 0x1c000
	v_add_u32_e32 v110, s59, v173
	v_add_u32_e32 v181, s68, v173
	ds_read_b128 v[98:101], v110
	ds_read_b128 v[102:105], v110 offset:1024
	ds_read_b128 v[106:109], v110 offset:2048
	ds_read_b128 v[110:113], v110 offset:3072
	ds_read_b128 v[164:167], v181
	ds_read_b128 v[168:171], v181 offset:1024
	ds_read_b128 v[182:185], v181 offset:2048
	ds_read_b128 v[186:189], v181 offset:3072
	s_add_u32 s30, s30, 0x80000
	s_addc_u32 s31, s31, 0
	s_mov_b32 m0, s38
	v_lshl_add_u64 v[230:231], s[30:31], 0, v[154:155]
	ds_read_b128 v[190:193], v177 offset:32768
	ds_read_b128 v[194:197], v177 offset:33792
	ds_read_b128 v[198:201], v177 offset:34816
	ds_read_b128 v[202:205], v177 offset:35840
	ds_read_b128 v[206:209], v177 offset:36864
	ds_read_b128 v[210:213], v177 offset:37888
	ds_read_b128 v[214:217], v177 offset:38912
	ds_read_b128 v[218:221], v177 offset:39936
	global_load_lds_dwordx4 v[230:231], off
	v_lshl_add_u64 v[230:231], s[30:31], 0, v[150:151]
	s_mov_b32 m0, s39
	s_nop 0
	global_load_lds_dwordx4 v[230:231], off
	s_waitcnt vmcnt(8)
	s_waitcnt lgkmcnt(0)
	s_setprio 1
	s_barrier
	v_mfma_f32_16x16x32_bf16 v[142:145], v[98:101], v[190:193], v[142:145]
	v_mfma_f32_16x16x32_bf16 v[138:141], v[106:109], v[190:193], v[138:141]
	v_mfma_f32_16x16x32_bf16 v[126:129], v[98:101], v[198:201], v[126:129]
	v_mfma_f32_16x16x32_bf16 v[122:125], v[106:109], v[198:201], v[122:125]
	v_mfma_f32_16x16x32_bf16 v[94:97], v[98:101], v[206:209], v[94:97]
	v_mfma_f32_16x16x32_bf16 v[90:93], v[106:109], v[206:209], v[90:93]
	v_mfma_f32_16x16x32_bf16 v[78:81], v[98:101], v[214:217], v[78:81]
	v_mfma_f32_16x16x32_bf16 v[74:77], v[106:109], v[214:217], v[74:77]
	v_mfma_f32_16x16x32_bf16 v[142:145], v[102:105], v[194:197], v[142:145]
	v_mfma_f32_16x16x32_bf16 v[138:141], v[110:113], v[194:197], v[138:141]
	v_mfma_f32_16x16x32_bf16 v[126:129], v[102:105], v[202:205], v[126:129]
	v_mfma_f32_16x16x32_bf16 v[122:125], v[110:113], v[202:205], v[122:125]
	v_mfma_f32_16x16x32_bf16 v[94:97], v[102:105], v[210:213], v[94:97]
	v_mfma_f32_16x16x32_bf16 v[90:93], v[110:113], v[210:213], v[90:93]
	v_mfma_f32_16x16x32_bf16 v[78:81], v[102:105], v[218:221], v[78:81]
	v_mfma_f32_16x16x32_bf16 v[74:77], v[110:113], v[218:221], v[74:77]
	v_mfma_f32_16x16x32_bf16 v[134:137], v[164:167], v[190:193], v[134:137]
	v_mfma_f32_16x16x32_bf16 v[130:133], v[182:185], v[190:193], v[130:133]
	v_mfma_f32_16x16x32_bf16 v[118:121], v[164:167], v[198:201], v[118:121]
	v_mfma_f32_16x16x32_bf16 v[114:117], v[182:185], v[198:201], v[114:117]
	v_mfma_f32_16x16x32_bf16 v[86:89], v[164:167], v[206:209], v[86:89]
	v_mfma_f32_16x16x32_bf16 v[82:85], v[182:185], v[206:209], v[82:85]
	v_mfma_f32_16x16x32_bf16 v[70:73], v[164:167], v[214:217], v[70:73]
	v_mfma_f32_16x16x32_bf16 v[66:69], v[182:185], v[214:217], v[66:69]
	v_mfma_f32_16x16x32_bf16 v[134:137], v[168:171], v[194:197], v[134:137]
	v_mfma_f32_16x16x32_bf16 v[130:133], v[186:189], v[194:197], v[130:133]
	v_mfma_f32_16x16x32_bf16 v[118:121], v[168:171], v[202:205], v[118:121]
	v_mfma_f32_16x16x32_bf16 v[114:117], v[186:189], v[202:205], v[114:117]
	v_mfma_f32_16x16x32_bf16 v[86:89], v[168:171], v[210:213], v[86:89]
	v_mfma_f32_16x16x32_bf16 v[82:85], v[186:189], v[210:213], v[82:85]
	v_mfma_f32_16x16x32_bf16 v[70:73], v[168:171], v[218:221], v[70:73]
	v_mfma_f32_16x16x32_bf16 v[66:69], v[186:189], v[218:221], v[66:69]
	s_barrier
	s_setprio 0
	s_add_i32 s30, s59, s33
	v_lshl_add_u64 v[222:223], v[222:223], 0, s[8:9]
	s_mov_b32 m0, s30
	ds_read_b128 v[190:193], v177 offset:49152
	ds_read_b128 v[194:197], v177 offset:50176
	ds_read_b128 v[198:201], v177 offset:51200
	ds_read_b128 v[202:205], v177 offset:52224
	ds_read_b128 v[206:209], v177 offset:53248
	ds_read_b128 v[210:213], v177 offset:54272
	ds_read_b128 v[214:217], v177 offset:55296
	ds_read_b128 v[218:221], v177 offset:56320
	global_load_lds_dwordx4 v[222:223], off
	s_add_i32 m0, s30, 0x2000
	s_add_u32 s28, s28, 0x80080
	v_lshl_add_u64 v[222:223], v[224:225], 0, s[8:9]
	s_addc_u32 s29, s29, 0
	s_add_i32 s30, s68, s33
	global_load_lds_dwordx4 v[222:223], off
	v_lshl_add_u64 v[222:223], s[28:29], 0, v[152:153]
	s_mov_b32 m0, s30
	s_nop 0
	global_load_lds_dwordx4 v[222:223], off
	v_lshl_add_u64 v[222:223], s[28:29], 0, v[148:149]
	s_add_i32 m0, s30, 0x2000
	s_nop 0
	global_load_lds_dwordx4 v[222:223], off
	v_lshl_add_u64 v[222:223], v[226:227], 0, s[8:9]
	s_mov_b32 m0, s41
	s_nop 0
	global_load_lds_dwordx4 v[222:223], off
	v_lshl_add_u64 v[222:223], v[228:229], 0, s[8:9]
	s_mov_b32 m0, s42
	s_nop 0
	global_load_lds_dwordx4 v[222:223], off
	s_waitcnt vmcnt(8)
	s_waitcnt lgkmcnt(0)
	s_nop 0
	s_setprio 1
	s_barrier
	v_mfma_f32_16x16x32_bf16 v[62:65], v[98:101], v[190:193], v[62:65]
	v_mfma_f32_16x16x32_bf16 v[58:61], v[106:109], v[190:193], v[58:61]
	v_mfma_f32_16x16x32_bf16 v[46:49], v[98:101], v[198:201], v[46:49]
	v_mfma_f32_16x16x32_bf16 v[42:45], v[106:109], v[198:201], v[42:45]
	v_mfma_f32_16x16x32_bf16 v[30:33], v[98:101], v[206:209], v[30:33]
	v_mfma_f32_16x16x32_bf16 v[26:29], v[106:109], v[206:209], v[26:29]
	v_mfma_f32_16x16x32_bf16 v[14:17], v[98:101], v[214:217], v[14:17]
	v_mfma_f32_16x16x32_bf16 v[10:13], v[106:109], v[214:217], v[10:13]
	v_mfma_f32_16x16x32_bf16 v[62:65], v[102:105], v[194:197], v[62:65]
	v_mfma_f32_16x16x32_bf16 v[58:61], v[110:113], v[194:197], v[58:61]
	v_mfma_f32_16x16x32_bf16 v[46:49], v[102:105], v[202:205], v[46:49]
	v_mfma_f32_16x16x32_bf16 v[42:45], v[110:113], v[202:205], v[42:45]
	v_mfma_f32_16x16x32_bf16 v[30:33], v[102:105], v[210:213], v[30:33]
	v_mfma_f32_16x16x32_bf16 v[26:29], v[110:113], v[210:213], v[26:29]
	v_mfma_f32_16x16x32_bf16 v[14:17], v[102:105], v[218:221], v[14:17]
	v_mfma_f32_16x16x32_bf16 v[10:13], v[110:113], v[218:221], v[10:13]
	v_mfma_f32_16x16x32_bf16 v[54:57], v[164:167], v[190:193], v[54:57]
	v_mfma_f32_16x16x32_bf16 v[50:53], v[182:185], v[190:193], v[50:53]
	v_mfma_f32_16x16x32_bf16 v[38:41], v[164:167], v[198:201], v[38:41]
	v_mfma_f32_16x16x32_bf16 v[34:37], v[182:185], v[198:201], v[34:37]
	v_mfma_f32_16x16x32_bf16 v[22:25], v[164:167], v[206:209], v[22:25]
	v_mfma_f32_16x16x32_bf16 v[18:21], v[182:185], v[206:209], v[18:21]
	v_mfma_f32_16x16x32_bf16 v[6:9], v[164:167], v[214:217], v[6:9]
	v_mfma_f32_16x16x32_bf16 v[2:5], v[182:185], v[214:217], v[2:5]
	v_mfma_f32_16x16x32_bf16 v[54:57], v[168:171], v[194:197], v[54:57]
	v_mfma_f32_16x16x32_bf16 v[50:53], v[186:189], v[194:197], v[50:53]
	v_mfma_f32_16x16x32_bf16 v[38:41], v[168:171], v[202:205], v[38:41]
	v_mfma_f32_16x16x32_bf16 v[34:37], v[186:189], v[202:205], v[34:37]
	v_mfma_f32_16x16x32_bf16 v[22:25], v[168:171], v[210:213], v[22:25]
	v_mfma_f32_16x16x32_bf16 v[18:21], v[186:189], v[210:213], v[18:21]
	v_mfma_f32_16x16x32_bf16 v[6:9], v[168:171], v[218:221], v[6:9]
	v_mfma_f32_16x16x32_bf16 v[2:5], v[186:189], v[218:221], v[2:5]
	s_barrier
	s_setprio 0
	s_add_i32 s58, s58, 2
	s_add_u32 s26, s26, 0x100
	s_addc_u32 s27, s27, 0
	s_add_u32 s56, s56, 0x100
	s_addc_u32 s57, s57, 0
	s_cmp_gt_u32 s58, 29
	s_cbranch_scc0 .LBB0_1208
	s_and_b64 vcc, exec, s[16:17]
	s_cbranch_vccz .LBB0_1211
	s_barrier

.LBB0_1284:
	ds_read_b128 v[122:125], v173
	ds_read_b128 v[126:129], v173 offset:1024
	ds_read_b128 v[130:133], v173 offset:2048
	ds_read_b128 v[134:137], v173 offset:3072
	ds_read_b128 v[164:167], v174
	ds_read_b128 v[180:183], v174 offset:1024
	ds_read_b128 v[184:187], v174 offset:2048
	ds_read_b128 v[188:191], v174 offset:3072
	s_add_u32 s28, s26, 0x100
	s_addc_u32 s29, s27, 0
	s_cmpk_eq_i32 s60, 0x54
	s_cselect_b32 s35, s5, s29
	s_cselect_b32 s34, s4, s28
	s_cselect_b32 s31, s25, s59
	s_cselect_b32 s30, s24, s58
	v_lshl_add_u64 v[168:169], s[26:27], 0, v[156:157]
	s_add_i32 m0, s38, 0xc000
	ds_read_b128 v[192:195], v175
	ds_read_b128 v[196:199], v175 offset:1024
	ds_read_b128 v[200:203], v175 offset:2048
	ds_read_b128 v[204:207], v175 offset:3072
	ds_read_b128 v[208:211], v175 offset:4096
	ds_read_b128 v[212:215], v175 offset:5120
	ds_read_b128 v[216:219], v175 offset:6144
	ds_read_b128 v[220:223], v175 offset:7168
	global_load_lds_dwordx4 v[168:169], off
	v_lshl_add_u64 v[168:169], s[26:27], 0, v[158:159]
	s_add_i32 m0, s38, 0xe000
	s_nop 0
	global_load_lds_dwordx4 v[168:169], off
	s_waitcnt vmcnt(8)
	s_waitcnt lgkmcnt(0)
	s_nop 0
	s_setprio 1
	s_barrier
	v_mfma_f32_16x16x32_bf16 v[142:145], v[122:125], v[192:195], v[142:145]
	v_mfma_f32_16x16x32_bf16 v[138:141], v[130:133], v[192:195], v[138:141]
	v_mfma_f32_16x16x32_bf16 v[110:113], v[122:125], v[200:203], v[110:113]
	v_mfma_f32_16x16x32_bf16 v[106:109], v[130:133], v[200:203], v[106:109]
	v_mfma_f32_16x16x32_bf16 v[94:97], v[122:125], v[208:211], v[94:97]
	v_mfma_f32_16x16x32_bf16 v[90:93], v[130:133], v[208:211], v[90:93]
	v_mfma_f32_16x16x32_bf16 v[78:81], v[122:125], v[216:219], v[78:81]
	v_mfma_f32_16x16x32_bf16 v[74:77], v[130:133], v[216:219], v[74:77]
	v_mfma_f32_16x16x32_bf16 v[142:145], v[126:129], v[196:199], v[142:145]
	v_mfma_f32_16x16x32_bf16 v[138:141], v[134:137], v[196:199], v[138:141]
	v_mfma_f32_16x16x32_bf16 v[110:113], v[126:129], v[204:207], v[110:113]
	v_mfma_f32_16x16x32_bf16 v[106:109], v[134:137], v[204:207], v[106:109]
	v_mfma_f32_16x16x32_bf16 v[94:97], v[126:129], v[212:215], v[94:97]
	v_mfma_f32_16x16x32_bf16 v[90:93], v[134:137], v[212:215], v[90:93]
	v_mfma_f32_16x16x32_bf16 v[78:81], v[126:129], v[220:223], v[78:81]
	v_mfma_f32_16x16x32_bf16 v[74:77], v[134:137], v[220:223], v[74:77]
	v_mfma_f32_16x16x32_bf16 v[118:121], v[164:167], v[192:195], v[118:121]
	v_mfma_f32_16x16x32_bf16 v[114:117], v[184:187], v[192:195], v[114:117]
	v_mfma_f32_16x16x32_bf16 v[102:105], v[164:167], v[200:203], v[102:105]
	v_mfma_f32_16x16x32_bf16 v[98:101], v[184:187], v[200:203], v[98:101]
	v_mfma_f32_16x16x32_bf16 v[86:89], v[164:167], v[208:211], v[86:89]
	v_mfma_f32_16x16x32_bf16 v[82:85], v[184:187], v[208:211], v[82:85]
	v_mfma_f32_16x16x32_bf16 v[70:73], v[164:167], v[216:219], v[70:73]
	v_mfma_f32_16x16x32_bf16 v[66:69], v[184:187], v[216:219], v[66:69]
	v_mfma_f32_16x16x32_bf16 v[118:121], v[180:183], v[196:199], v[118:121]
	v_mfma_f32_16x16x32_bf16 v[114:117], v[188:191], v[196:199], v[114:117]
	v_mfma_f32_16x16x32_bf16 v[102:105], v[180:183], v[204:207], v[102:105]
	v_mfma_f32_16x16x32_bf16 v[98:101], v[188:191], v[204:207], v[98:101]
	v_mfma_f32_16x16x32_bf16 v[86:89], v[180:183], v[212:215], v[86:89]
	v_mfma_f32_16x16x32_bf16 v[82:85], v[188:191], v[212:215], v[82:85]
	v_mfma_f32_16x16x32_bf16 v[70:73], v[180:183], v[220:223], v[70:73]
	v_mfma_f32_16x16x32_bf16 v[66:69], v[188:191], v[220:223], v[66:69]
	s_barrier
	s_setprio 0
	s_add_i32 s26, s48, s33
	v_lshl_add_u64 v[168:169], s[30:31], 0, v[152:153]
	s_mov_b32 m0, s26
	ds_read_b128 v[192:195], v175 offset:16384
	ds_read_b128 v[196:199], v175 offset:17408
	ds_read_b128 v[200:203], v175 offset:18432
	ds_read_b128 v[204:207], v175 offset:19456
	ds_read_b128 v[208:211], v175 offset:20480
	ds_read_b128 v[212:215], v175 offset:21504
	ds_read_b128 v[216:219], v175 offset:22528
	ds_read_b128 v[220:223], v175 offset:23552
	global_load_lds_dwordx4 v[168:169], off
	s_add_i32 m0, s26, 0x2000
	s_add_u32 s26, s30, 0x160000
	v_lshl_add_u64 v[176:177], s[30:31], 0, v[148:149]
	s_addc_u32 s27, s31, 0
	s_add_i32 s61, s49, s33
	global_load_lds_dwordx4 v[176:177], off
	v_lshl_add_u64 v[224:225], s[26:27], 0, v[152:153]
	s_mov_b32 m0, s61
	v_lshl_add_u64 v[226:227], s[34:35], 0, v[150:151]
	global_load_lds_dwordx4 v[224:225], off
	v_lshl_add_u64 v[224:225], s[26:27], 0, v[148:149]
	s_add_i32 m0, s61, 0x2000
	s_nop 0
	global_load_lds_dwordx4 v[224:225], off
	v_lshl_add_u64 v[224:225], s[34:35], 0, v[154:155]
	s_mov_b32 m0, s38
	s_nop 0
	global_load_lds_dwordx4 v[224:225], off
	s_mov_b32 m0, s39
	s_nop 0
	global_load_lds_dwordx4 v[226:227], off
	s_waitcnt vmcnt(8)
	s_waitcnt lgkmcnt(0)
	s_setprio 1
	s_barrier
	v_mfma_f32_16x16x32_bf16 v[62:65], v[122:125], v[192:195], v[62:65]
	v_mfma_f32_16x16x32_bf16 v[58:61], v[130:133], v[192:195], v[58:61]
	v_mfma_f32_16x16x32_bf16 v[46:49], v[122:125], v[200:203], v[46:49]
	v_mfma_f32_16x16x32_bf16 v[42:45], v[130:133], v[200:203], v[42:45]
	v_mfma_f32_16x16x32_bf16 v[30:33], v[122:125], v[208:211], v[30:33]
	v_mfma_f32_16x16x32_bf16 v[26:29], v[130:133], v[208:211], v[26:29]
	v_mfma_f32_16x16x32_bf16 v[14:17], v[122:125], v[216:219], v[14:17]
	v_mfma_f32_16x16x32_bf16 v[10:13], v[130:133], v[216:219], v[10:13]
	v_mfma_f32_16x16x32_bf16 v[62:65], v[126:129], v[196:199], v[62:65]
	v_mfma_f32_16x16x32_bf16 v[58:61], v[134:137], v[196:199], v[58:61]
	v_mfma_f32_16x16x32_bf16 v[46:49], v[126:129], v[204:207], v[46:49]
	v_mfma_f32_16x16x32_bf16 v[42:45], v[134:137], v[204:207], v[42:45]
	v_mfma_f32_16x16x32_bf16 v[30:33], v[126:129], v[212:215], v[30:33]
	v_mfma_f32_16x16x32_bf16 v[26:29], v[134:137], v[212:215], v[26:29]
	v_mfma_f32_16x16x32_bf16 v[14:17], v[126:129], v[220:223], v[14:17]
	v_mfma_f32_16x16x32_bf16 v[10:13], v[134:137], v[220:223], v[10:13]
	v_mfma_f32_16x16x32_bf16 v[54:57], v[164:167], v[192:195], v[54:57]
	v_mfma_f32_16x16x32_bf16 v[50:53], v[184:187], v[192:195], v[50:53]
	v_mfma_f32_16x16x32_bf16 v[38:41], v[164:167], v[200:203], v[38:41]
	v_mfma_f32_16x16x32_bf16 v[34:37], v[184:187], v[200:203], v[34:37]
	v_mfma_f32_16x16x32_bf16 v[22:25], v[164:167], v[208:211], v[22:25]
	v_mfma_f32_16x16x32_bf16 v[18:21], v[184:187], v[208:211], v[18:21]
	v_mfma_f32_16x16x32_bf16 v[6:9], v[164:167], v[216:219], v[6:9]
	v_mfma_f32_16x16x32_bf16 v[2:5], v[184:187], v[216:219], v[2:5]
	v_mfma_f32_16x16x32_bf16 v[54:57], v[180:183], v[196:199], v[54:57]
	v_mfma_f32_16x16x32_bf16 v[50:53], v[188:191], v[196:199], v[50:53]
	v_mfma_f32_16x16x32_bf16 v[38:41], v[180:183], v[204:207], v[38:41]
	v_mfma_f32_16x16x32_bf16 v[34:37], v[188:191], v[204:207], v[34:37]
	v_mfma_f32_16x16x32_bf16 v[22:25], v[180:183], v[212:215], v[22:25]
	v_mfma_f32_16x16x32_bf16 v[18:21], v[188:191], v[212:215], v[18:21]
	v_mfma_f32_16x16x32_bf16 v[6:9], v[180:183], v[220:223], v[6:9]
	v_mfma_f32_16x16x32_bf16 v[2:5], v[188:191], v[220:223], v[2:5]
	s_barrier
	s_setprio 0
	s_add_i32 s61, 0, 0x18000
	s_add_i32 s68, 0, 0x1c000
	v_add_u32_e32 v134, s61, v171
	v_add_u32_e32 v179, s68, v171
	ds_read_b128 v[122:125], v134
	ds_read_b128 v[126:129], v134 offset:1024
	ds_read_b128 v[130:133], v134 offset:2048
	ds_read_b128 v[134:137], v134 offset:3072
	ds_read_b128 v[164:167], v179
	ds_read_b128 v[180:183], v179 offset:1024
	ds_read_b128 v[184:187], v179 offset:2048
	ds_read_b128 v[188:191], v179 offset:3072
	s_add_u32 s26, s34, 0x160000
	s_addc_u32 s27, s35, 0
	s_mov_b32 m0, s40
	v_lshl_add_u64 v[228:229], s[26:27], 0, v[154:155]
	ds_read_b128 v[192:195], v175 offset:32768
	ds_read_b128 v[196:199], v175 offset:33792
	ds_read_b128 v[200:203], v175 offset:34816
	ds_read_b128 v[204:207], v175 offset:35840
	ds_read_b128 v[208:211], v175 offset:36864
	ds_read_b128 v[212:215], v175 offset:37888
	ds_read_b128 v[216:219], v175 offset:38912
	ds_read_b128 v[220:223], v175 offset:39936
	global_load_lds_dwordx4 v[228:229], off
	v_lshl_add_u64 v[228:229], s[26:27], 0, v[150:151]
	s_mov_b32 m0, s41
	s_nop 0
	global_load_lds_dwordx4 v[228:229], off
	s_waitcnt vmcnt(8)
	s_waitcnt lgkmcnt(0)
	s_setprio 1
	s_barrier
	v_mfma_f32_16x16x32_bf16 v[142:145], v[122:125], v[192:195], v[142:145]
	v_mfma_f32_16x16x32_bf16 v[138:141], v[130:133], v[192:195], v[138:141]
	v_mfma_f32_16x16x32_bf16 v[110:113], v[122:125], v[200:203], v[110:113]
	v_mfma_f32_16x16x32_bf16 v[106:109], v[130:133], v[200:203], v[106:109]
	v_mfma_f32_16x16x32_bf16 v[94:97], v[122:125], v[208:211], v[94:97]
	v_mfma_f32_16x16x32_bf16 v[90:93], v[130:133], v[208:211], v[90:93]
	v_mfma_f32_16x16x32_bf16 v[78:81], v[122:125], v[216:219], v[78:81]
	v_mfma_f32_16x16x32_bf16 v[74:77], v[130:133], v[216:219], v[74:77]
	v_mfma_f32_16x16x32_bf16 v[142:145], v[126:129], v[196:199], v[142:145]
	v_mfma_f32_16x16x32_bf16 v[138:141], v[134:137], v[196:199], v[138:141]
	v_mfma_f32_16x16x32_bf16 v[110:113], v[126:129], v[204:207], v[110:113]
	v_mfma_f32_16x16x32_bf16 v[106:109], v[134:137], v[204:207], v[106:109]
	v_mfma_f32_16x16x32_bf16 v[94:97], v[126:129], v[212:215], v[94:97]
	v_mfma_f32_16x16x32_bf16 v[90:93], v[134:137], v[212:215], v[90:93]
	v_mfma_f32_16x16x32_bf16 v[78:81], v[126:129], v[220:223], v[78:81]
	v_mfma_f32_16x16x32_bf16 v[74:77], v[134:137], v[220:223], v[74:77]
	v_mfma_f32_16x16x32_bf16 v[118:121], v[164:167], v[192:195], v[118:121]
	v_mfma_f32_16x16x32_bf16 v[114:117], v[184:187], v[192:195], v[114:117]
	v_mfma_f32_16x16x32_bf16 v[102:105], v[164:167], v[200:203], v[102:105]
	v_mfma_f32_16x16x32_bf16 v[98:101], v[184:187], v[200:203], v[98:101]
	v_mfma_f32_16x16x32_bf16 v[86:89], v[164:167], v[208:211], v[86:89]
	v_mfma_f32_16x16x32_bf16 v[82:85], v[184:187], v[208:211], v[82:85]
	v_mfma_f32_16x16x32_bf16 v[70:73], v[164:167], v[216:219], v[70:73]
	v_mfma_f32_16x16x32_bf16 v[66:69], v[184:187], v[216:219], v[66:69]
	v_mfma_f32_16x16x32_bf16 v[118:121], v[180:183], v[196:199], v[118:121]
	v_mfma_f32_16x16x32_bf16 v[114:117], v[188:191], v[196:199], v[114:117]
	v_mfma_f32_16x16x32_bf16 v[102:105], v[180:183], v[204:207], v[102:105]
	v_mfma_f32_16x16x32_bf16 v[98:101], v[188:191], v[204:207], v[98:101]
	v_mfma_f32_16x16x32_bf16 v[86:89], v[180:183], v[212:215], v[86:89]
	v_mfma_f32_16x16x32_bf16 v[82:85], v[188:191], v[212:215], v[82:85]
	v_mfma_f32_16x16x32_bf16 v[70:73], v[180:183], v[220:223], v[70:73]
	v_mfma_f32_16x16x32_bf16 v[66:69], v[188:191], v[220:223], v[66:69]
	s_barrier
	s_setprio 0
	s_add_i32 s26, s61, s33
	v_lshl_add_u64 v[168:169], v[168:169], 0, s[8:9]
	s_mov_b32 m0, s26
	ds_read_b128 v[192:195], v175 offset:49152
	ds_read_b128 v[196:199], v175 offset:50176
	ds_read_b128 v[200:203], v175 offset:51200
	ds_read_b128 v[204:207], v175 offset:52224
	ds_read_b128 v[208:211], v175 offset:53248
	ds_read_b128 v[212:215], v175 offset:54272
	ds_read_b128 v[216:219], v175 offset:55296
	ds_read_b128 v[220:223], v175 offset:56320
	global_load_lds_dwordx4 v[168:169], off
	s_add_i32 m0, s26, 0x2000
	s_add_u32 s26, s30, 0x160080
	v_lshl_add_u64 v[168:169], v[176:177], 0, s[8:9]
	s_addc_u32 s27, s31, 0
	s_add_i32 s30, s68, s33
	global_load_lds_dwordx4 v[168:169], off
	v_lshl_add_u64 v[168:169], s[26:27], 0, v[152:153]
	s_mov_b32 m0, s30
	s_nop 0
	global_load_lds_dwordx4 v[168:169], off
	v_lshl_add_u64 v[168:169], s[26:27], 0, v[148:149]
	s_add_i32 m0, s30, 0x2000
	s_nop 0
	global_load_lds_dwordx4 v[168:169], off
	v_lshl_add_u64 v[168:169], v[224:225], 0, s[8:9]
	s_mov_b32 m0, s43
	s_nop 0
	global_load_lds_dwordx4 v[168:169], off
	v_lshl_add_u64 v[168:169], v[226:227], 0, s[8:9]
	s_mov_b32 m0, s44
	s_nop 0
	global_load_lds_dwordx4 v[168:169], off
	s_waitcnt vmcnt(8)
	s_waitcnt lgkmcnt(0)
	s_nop 0
	s_setprio 1
	s_barrier
	v_mfma_f32_16x16x32_bf16 v[62:65], v[122:125], v[192:195], v[62:65]
	v_mfma_f32_16x16x32_bf16 v[58:61], v[130:133], v[192:195], v[58:61]
	v_mfma_f32_16x16x32_bf16 v[46:49], v[122:125], v[200:203], v[46:49]
	v_mfma_f32_16x16x32_bf16 v[42:45], v[130:133], v[200:203], v[42:45]
	v_mfma_f32_16x16x32_bf16 v[30:33], v[122:125], v[208:211], v[30:33]
	v_mfma_f32_16x16x32_bf16 v[26:29], v[130:133], v[208:211], v[26:29]
	v_mfma_f32_16x16x32_bf16 v[14:17], v[122:125], v[216:219], v[14:17]
	v_mfma_f32_16x16x32_bf16 v[10:13], v[130:133], v[216:219], v[10:13]
	v_mfma_f32_16x16x32_bf16 v[62:65], v[126:129], v[196:199], v[62:65]
	v_mfma_f32_16x16x32_bf16 v[58:61], v[134:137], v[196:199], v[58:61]
	v_mfma_f32_16x16x32_bf16 v[46:49], v[126:129], v[204:207], v[46:49]
	v_mfma_f32_16x16x32_bf16 v[42:45], v[134:137], v[204:207], v[42:45]
	v_mfma_f32_16x16x32_bf16 v[30:33], v[126:129], v[212:215], v[30:33]
	v_mfma_f32_16x16x32_bf16 v[26:29], v[134:137], v[212:215], v[26:29]
	v_mfma_f32_16x16x32_bf16 v[14:17], v[126:129], v[220:223], v[14:17]
	v_mfma_f32_16x16x32_bf16 v[10:13], v[134:137], v[220:223], v[10:13]
	v_mfma_f32_16x16x32_bf16 v[54:57], v[164:167], v[192:195], v[54:57]
	v_mfma_f32_16x16x32_bf16 v[50:53], v[184:187], v[192:195], v[50:53]
	v_mfma_f32_16x16x32_bf16 v[38:41], v[164:167], v[200:203], v[38:41]
	v_mfma_f32_16x16x32_bf16 v[34:37], v[184:187], v[200:203], v[34:37]
	v_mfma_f32_16x16x32_bf16 v[22:25], v[164:167], v[208:211], v[22:25]
	v_mfma_f32_16x16x32_bf16 v[18:21], v[184:187], v[208:211], v[18:21]
	v_mfma_f32_16x16x32_bf16 v[6:9], v[164:167], v[216:219], v[6:9]
	v_mfma_f32_16x16x32_bf16 v[2:5], v[184:187], v[216:219], v[2:5]
	v_mfma_f32_16x16x32_bf16 v[54:57], v[180:183], v[196:199], v[54:57]
	v_mfma_f32_16x16x32_bf16 v[50:53], v[188:191], v[196:199], v[50:53]
	v_mfma_f32_16x16x32_bf16 v[38:41], v[180:183], v[204:207], v[38:41]
	v_mfma_f32_16x16x32_bf16 v[34:37], v[188:191], v[204:207], v[34:37]
	v_mfma_f32_16x16x32_bf16 v[22:25], v[180:183], v[212:215], v[22:25]
	v_mfma_f32_16x16x32_bf16 v[18:21], v[188:191], v[212:215], v[18:21]
	v_mfma_f32_16x16x32_bf16 v[6:9], v[180:183], v[220:223], v[6:9]
	v_mfma_f32_16x16x32_bf16 v[2:5], v[188:191], v[220:223], v[2:5]
	s_barrier
	s_setprio 0
	s_add_i32 s60, s60, 2
	s_add_u32 s58, s58, 0x100
	s_addc_u32 s59, s59, 0
	s_cmpk_gt_u32 s60, 0x55
	s_mov_b64 s[26:27], s[28:29]
	s_cbranch_scc0 .LBB0_1284
	s_and_b64 vcc, exec, s[12:13]
	s_cbranch_vccz .LBB0_1287
	s_barrier
